# speedup vs baseline: 1.0782x; 1.0037x over previous
; template <int NS, bool LN, bool WF32, bool WBF, int SKMODE>
; DI_ void row_pass(const float* Xin, float* Xout, bf16_t* XBo, const float* g, const float* b, const float* WsT, float* sk_out, const float* sk_bias, int row0, int nrows, int gw, int NGW, int lane) {
;     ...
;     if (row0 + gw < row0 + nrows) { const f32x4* xr = (const f32x4*)(Xin + (size_t)(row0 + gw) * D) + lane;
; #pragma unroll
;         for (int j = 0; j < 4; ++j) nv[j] = xr[64 * j]; }
;     for (int row = row0 + gw; row < row0 + nrows; row += NGW) {
;         f32x4 v[4];
; #pragma unroll
;         for (int j = 0; j < 4; ++j) v[j] = nv[j];
;         if (row + NGW < row0 + nrows) { const f32x4* xr = (const f32x4*)(Xin + (size_t)(row + NGW) * D) + lane;
; #pragma unroll
;             for (int j = 0; j < 4; ++j) nv[j] = xr[64 * j]; }
;         if (LN) {
;             float s = 0.f;
; #pragma unroll
;             for (int j = 0; j < 4; ++j) s += (v[j][0] + v[j][1]) + (v[j][2] + v[j][3]);
;             const float mean = wave_sum(s) * (1.f / D); float s2 = 0.f;
; #pragma unroll
;             for (int j = 0; j < 4; ++j) { v[j] = v[j] - mean; s2 += (v[j][0] * v[j][0] + v[j][1] * v[j][1]) + (v[j][2] * v[j][2] + v[j][3] * v[j][3]); }
;             const float rstd = 1.f / sqrtf(wave_sum(s2) * (1.f / D) + LN_EPS);
; #pragma unroll
;             for (int j = 0; j < 4; ++j) { const f32x4 gg = ((const f32x4*)g)[lane + 64 * j], bb = ((const f32x4*)b)[lane + 64 * j]; v[j] = v[j] * rstd * gg + bb; }
;         }
;         if (WF32) {
;             f32x4* xo = (f32x4*)(Xout + (size_t)row * D) + lane;
; #pragma unroll
;             for (int j = 0; j < 4; ++j) xo[64 * j] = v[j];
;         }
;         if (WBF) {
;             u32x2* xo = (u32x2*)(XBo + (size_t)row * D) + lane;
; #pragma unroll
;             for (int j = 0; j < 4; ++j) { u32x2 w; w.x = pk2(v[j][0], v[j][1]); w.y = pk2(v[j][2], v[j][3]); xo[64 * j] = w; }
;         }
;         if (NS > 0) {
; #pragma unroll 1
;             for (int grp = 0; grp < NS / 8; ++grp) {
;                 float a[8];
; #pragma unroll
;                 for (int jc = 0; jc < 8; ++jc) {
;                     float s = 0.f;
; #pragma unroll
;                     for (int j = 0; j < 4; ++j) { const f32x4 w = *(const f32x4*)(WsT + (8 * grp + jc) * WST + 4 * (lane + 64 * j)); s += (v[j][0] * w[0] + v[j][1] * w[1]) + (v[j][2] * w[2] + v[j][3] * w[3]); }
.LBB0_40:
	s_or_b64 exec, exec, s[0:1]
	v_mov_b32_e32 v18, v187
	s_add_u32 s86, s90, 0x4000000
	s_waitcnt lgkmcnt(0)
	s_barrier
	s_addc_u32 s87, s91, 0
	v_readfirstlane_b32 s0, v18
	s_ashr_i32 s0, s0, 6
	s_add_i32 s20, s0, s95
	s_add_u32 s3, s90, 0x14500000
	s_addc_u32 s33, s91, 0
	s_cmpk_gt_i32 s20, 0x7fff
	v_mbcnt_lo_u32_b32 v149, -1, 0
	s_cbranch_scc1 .LBB0_50
	s_cmpk_lg_i32 s94, 0x800
	s_cbranch_scc1 .Lmy_p0_orig
	s_lshl_b32 s0, s20, 4
	v_and_b32_e32 v1, 63, v18
	v_and_b32_e32 v2, 15, v1
	v_lshrrev_b32_e32 v3, 4, v1
	v_add_u32_e32 v4, s0, v2
	v_lshlrev_b32_e32 v6, 12, v4
	v_lshl_add_u32 v6, v3, 5, v6
	v_mov_b32_e32 v7, 0
	v_lshl_add_u64 v[6:7], s[56:57], 0, v[6:7]
	v_lshlrev_b32_e32 v8, 11, v4
	v_lshl_add_u32 v8, v3, 4, v8
	v_mov_b32_e32 v9, 0
	v_lshl_add_u64 v[8:9], s[86:87], 0, v[8:9]
	v_mul_u32_u24_e32 v10, 0x1010, v2
	v_lshl_add_u32 v10, v3, 5, v10
	v_lshlrev_b32_e32 v11, 2, v2
	v_mov_b32_e32 v12, 0
	v_mov_b32_e32 v13, 0
	v_mov_b32_e32 v14, 0
	v_mov_b32_e32 v15, 0
	v_mov_b32_e32 v16, 0
	v_mov_b32_e32 v17, 0
	v_mov_b32_e32 v18, 0
	v_mov_b32_e32 v19, 0
	global_load_dwordx4 v[98:101], v[6:7], off
	global_load_dwordx4 v[102:105], v[6:7], off offset:16
	global_load_dwordx4 v[106:109], v[6:7], off offset:128
	global_load_dwordx4 v[110:113], v[6:7], off offset:144
	global_load_dwordx4 v[114:117], v[6:7], off offset:256
	global_load_dwordx4 v[118:121], v[6:7], off offset:272
	global_load_dwordx4 v[122:125], v[6:7], off offset:384
	global_load_dwordx4 v[126:129], v[6:7], off offset:400
	global_load_dwordx4 v[130:133], v[6:7], off offset:512
	global_load_dwordx4 v[134:137], v[6:7], off offset:528
	global_load_dwordx4 v[138:141], v[6:7], off offset:640
	global_load_dwordx4 v[142:145], v[6:7], off offset:656
	ds_read_b128 v[20:23], v10
	ds_read_b128 v[24:27], v10 offset:16
	ds_read_b128 v[28:31], v10 offset:128
	ds_read_b128 v[32:35], v10 offset:144
	global_load_dwordx4 v[150:153], v[6:7], off offset:768
	global_load_dwordx4 v[154:157], v[6:7], off offset:784
	global_load_dwordx4 v[158:161], v[6:7], off offset:896
	global_load_dwordx4 v[162:165], v[6:7], off offset:912
	ds_read_b128 v[36:39], v10 offset:256
	ds_read_b128 v[40:43], v10 offset:272
	ds_read_b128 v[44:47], v10 offset:384
	ds_read_b128 v[48:51], v10 offset:400
	s_waitcnt vmcnt(12)
	s_waitcnt lgkmcnt(4)
	v_mfma_f32_16x16x4_f32 v[12:15], v98, v20, v[12:15]
	v_mfma_f32_16x16x4_f32 v[16:19], v99, v21, v[16:19]
	v_cvt_pk_bf16_f32 v52, v98, v99
	v_mfma_f32_16x16x4_f32 v[12:15], v100, v22, v[12:15]
	v_mfma_f32_16x16x4_f32 v[16:19], v101, v23, v[16:19]
	v_cvt_pk_bf16_f32 v53, v100, v101
	v_mfma_f32_16x16x4_f32 v[12:15], v102, v24, v[12:15]
	v_mfma_f32_16x16x4_f32 v[16:19], v103, v25, v[16:19]
	v_cvt_pk_bf16_f32 v54, v102, v103
	v_mfma_f32_16x16x4_f32 v[12:15], v104, v26, v[12:15]
	v_mfma_f32_16x16x4_f32 v[16:19], v105, v27, v[16:19]
	v_cvt_pk_bf16_f32 v55, v104, v105
	v_mfma_f32_16x16x4_f32 v[12:15], v106, v28, v[12:15]
	v_mfma_f32_16x16x4_f32 v[16:19], v107, v29, v[16:19]
	v_cvt_pk_bf16_f32 v56, v106, v107
	v_mfma_f32_16x16x4_f32 v[12:15], v108, v30, v[12:15]
	v_mfma_f32_16x16x4_f32 v[16:19], v109, v31, v[16:19]
	v_cvt_pk_bf16_f32 v57, v108, v109
	v_mfma_f32_16x16x4_f32 v[12:15], v110, v32, v[12:15]
	v_mfma_f32_16x16x4_f32 v[16:19], v111, v33, v[16:19]
	v_cvt_pk_bf16_f32 v58, v110, v111
	v_mfma_f32_16x16x4_f32 v[12:15], v112, v34, v[12:15]
	v_mfma_f32_16x16x4_f32 v[16:19], v113, v35, v[16:19]
	v_cvt_pk_bf16_f32 v59, v112, v113
	global_store_dwordx4 v[8:9], v[52:55], off
	global_store_dwordx4 v[8:9], v[56:59], off offset:64
	global_load_dwordx4 v[98:101], v[6:7], off offset:1024
	global_load_dwordx4 v[102:105], v[6:7], off offset:1040
	global_load_dwordx4 v[106:109], v[6:7], off offset:1152
	global_load_dwordx4 v[110:113], v[6:7], off offset:1168
	ds_read_b128 v[20:23], v10 offset:512
	ds_read_b128 v[24:27], v10 offset:528
	ds_read_b128 v[28:31], v10 offset:640
	ds_read_b128 v[32:35], v10 offset:656
	s_waitcnt vmcnt(14)
	s_waitcnt lgkmcnt(4)
	v_mfma_f32_16x16x4_f32 v[12:15], v114, v36, v[12:15]
	v_mfma_f32_16x16x4_f32 v[16:19], v115, v37, v[16:19]
	v_cvt_pk_bf16_f32 v60, v114, v115
	v_mfma_f32_16x16x4_f32 v[12:15], v116, v38, v[12:15]
	v_mfma_f32_16x16x4_f32 v[16:19], v117, v39, v[16:19]
	v_cvt_pk_bf16_f32 v61, v116, v117
	v_mfma_f32_16x16x4_f32 v[12:15], v118, v40, v[12:15]
	v_mfma_f32_16x16x4_f32 v[16:19], v119, v41, v[16:19]
	v_cvt_pk_bf16_f32 v62, v118, v119
	v_mfma_f32_16x16x4_f32 v[12:15], v120, v42, v[12:15]
	v_mfma_f32_16x16x4_f32 v[16:19], v121, v43, v[16:19]
	v_cvt_pk_bf16_f32 v63, v120, v121
	v_mfma_f32_16x16x4_f32 v[12:15], v122, v44, v[12:15]
	v_mfma_f32_16x16x4_f32 v[16:19], v123, v45, v[16:19]
	v_cvt_pk_bf16_f32 v64, v122, v123
	v_mfma_f32_16x16x4_f32 v[12:15], v124, v46, v[12:15]
	v_mfma_f32_16x16x4_f32 v[16:19], v125, v47, v[16:19]
	v_cvt_pk_bf16_f32 v65, v124, v125
	v_mfma_f32_16x16x4_f32 v[12:15], v126, v48, v[12:15]
	v_mfma_f32_16x16x4_f32 v[16:19], v127, v49, v[16:19]
	v_cvt_pk_bf16_f32 v66, v126, v127
	v_mfma_f32_16x16x4_f32 v[12:15], v128, v50, v[12:15]
	v_mfma_f32_16x16x4_f32 v[16:19], v129, v51, v[16:19]
	v_cvt_pk_bf16_f32 v67, v128, v129
	global_store_dwordx4 v[8:9], v[60:63], off offset:128
	global_store_dwordx4 v[8:9], v[64:67], off offset:192
	global_load_dwordx4 v[114:117], v[6:7], off offset:1280
	global_load_dwordx4 v[118:121], v[6:7], off offset:1296
	global_load_dwordx4 v[122:125], v[6:7], off offset:1408
	global_load_dwordx4 v[126:129], v[6:7], off offset:1424
	ds_read_b128 v[36:39], v10 offset:768
	ds_read_b128 v[40:43], v10 offset:784
	ds_read_b128 v[44:47], v10 offset:896
	ds_read_b128 v[48:51], v10 offset:912
	s_waitcnt vmcnt(16)
	s_waitcnt lgkmcnt(4)
; DI_ unsigned pk2(float lo, float hi) { typedef float f2 __attribute__((ext_vector_type(2))); typedef __bf16 b2 __attribute__((ext_vector_type(2))); f2 v = {lo, hi}; b2 b = __builtin_convertvector(v, b2); return __builtin_bit_cast(unsigned, b); }
; template <int NS, bool LN, bool WF32, bool WBF, int SKMODE>
; DI_ void row_pass(const float* Xin, float* Xout, bf16_t* XBo, const float* g, const float* b, const float* WsT, float* sk_out, const float* sk_bias, int row0, int nrows, int gw, int NGW, int lane) {
;     ...
;         if (WBF) {
;             u32x2* xo = (u32x2*)(XBo + (size_t)row * D) + lane;
; #pragma unroll
;             for (int j = 0; j < 4; ++j) { u32x2 w; w.x = pk2(v[j][0], v[j][1]); w.y = pk2(v[j][2], v[j][3]); xo[64 * j] = w; }
;         }
;         if (NS > 0) {
; #pragma unroll 1
;             for (int grp = 0; grp < NS / 8; ++grp) {
;                 float a[8];
; #pragma unroll
;                 for (int jc = 0; jc < 8; ++jc) {
;                     float s = 0.f;
; #pragma unroll
;                     for (int j = 0; j < 4; ++j) { const f32x4 w = *(const f32x4*)(WsT + (8 * grp + jc) * WST + 4 * (lane + 64 * j)); s += (v[j][0] * w[0] + v[j][1] * w[1]) + (v[j][2] * w[2] + v[j][3] * w[3]); }
	v_mfma_f32_16x16x4_f32 v[12:15], v130, v20, v[12:15]
	v_mfma_f32_16x16x4_f32 v[16:19], v131, v21, v[16:19]
	v_cvt_pk_bf16_f32 v52, v130, v131
	v_mfma_f32_16x16x4_f32 v[12:15], v132, v22, v[12:15]
	v_mfma_f32_16x16x4_f32 v[16:19], v133, v23, v[16:19]
	v_cvt_pk_bf16_f32 v53, v132, v133
	v_mfma_f32_16x16x4_f32 v[12:15], v134, v24, v[12:15]
	v_mfma_f32_16x16x4_f32 v[16:19], v135, v25, v[16:19]
	v_cvt_pk_bf16_f32 v54, v134, v135
	v_mfma_f32_16x16x4_f32 v[12:15], v136, v26, v[12:15]
	v_mfma_f32_16x16x4_f32 v[16:19], v137, v27, v[16:19]
	v_cvt_pk_bf16_f32 v55, v136, v137
	v_mfma_f32_16x16x4_f32 v[12:15], v138, v28, v[12:15]
	v_mfma_f32_16x16x4_f32 v[16:19], v139, v29, v[16:19]
	v_cvt_pk_bf16_f32 v56, v138, v139
	v_mfma_f32_16x16x4_f32 v[12:15], v140, v30, v[12:15]
	v_mfma_f32_16x16x4_f32 v[16:19], v141, v31, v[16:19]
	v_cvt_pk_bf16_f32 v57, v140, v141
	v_mfma_f32_16x16x4_f32 v[12:15], v142, v32, v[12:15]
	v_mfma_f32_16x16x4_f32 v[16:19], v143, v33, v[16:19]
	v_cvt_pk_bf16_f32 v58, v142, v143
	v_mfma_f32_16x16x4_f32 v[12:15], v144, v34, v[12:15]
	v_mfma_f32_16x16x4_f32 v[16:19], v145, v35, v[16:19]
	v_cvt_pk_bf16_f32 v59, v144, v145
	global_store_dwordx4 v[8:9], v[52:55], off offset:256
	global_store_dwordx4 v[8:9], v[56:59], off offset:320
	global_load_dwordx4 v[130:133], v[6:7], off offset:1536
	global_load_dwordx4 v[134:137], v[6:7], off offset:1552
	global_load_dwordx4 v[138:141], v[6:7], off offset:1664
	global_load_dwordx4 v[142:145], v[6:7], off offset:1680
	ds_read_b128 v[20:23], v10 offset:1024
	ds_read_b128 v[24:27], v10 offset:1040
	ds_read_b128 v[28:31], v10 offset:1152
	ds_read_b128 v[32:35], v10 offset:1168
	s_waitcnt vmcnt(18)
	s_waitcnt lgkmcnt(4)
	v_mfma_f32_16x16x4_f32 v[12:15], v150, v36, v[12:15]
	v_mfma_f32_16x16x4_f32 v[16:19], v151, v37, v[16:19]
	v_cvt_pk_bf16_f32 v60, v150, v151
	v_mfma_f32_16x16x4_f32 v[12:15], v152, v38, v[12:15]
	v_mfma_f32_16x16x4_f32 v[16:19], v153, v39, v[16:19]
	v_cvt_pk_bf16_f32 v61, v152, v153
	v_mfma_f32_16x16x4_f32 v[12:15], v154, v40, v[12:15]
	v_mfma_f32_16x16x4_f32 v[16:19], v155, v41, v[16:19]
	v_cvt_pk_bf16_f32 v62, v154, v155
	v_mfma_f32_16x16x4_f32 v[12:15], v156, v42, v[12:15]
	v_mfma_f32_16x16x4_f32 v[16:19], v157, v43, v[16:19]
	v_cvt_pk_bf16_f32 v63, v156, v157
	v_mfma_f32_16x16x4_f32 v[12:15], v158, v44, v[12:15]
	v_mfma_f32_16x16x4_f32 v[16:19], v159, v45, v[16:19]
	v_cvt_pk_bf16_f32 v64, v158, v159
	v_mfma_f32_16x16x4_f32 v[12:15], v160, v46, v[12:15]
	v_mfma_f32_16x16x4_f32 v[16:19], v161, v47, v[16:19]
	v_cvt_pk_bf16_f32 v65, v160, v161
	v_mfma_f32_16x16x4_f32 v[12:15], v162, v48, v[12:15]
	v_mfma_f32_16x16x4_f32 v[16:19], v163, v49, v[16:19]
	v_cvt_pk_bf16_f32 v66, v162, v163
	v_mfma_f32_16x16x4_f32 v[12:15], v164, v50, v[12:15]
	v_mfma_f32_16x16x4_f32 v[16:19], v165, v51, v[16:19]
	v_cvt_pk_bf16_f32 v67, v164, v165
	global_store_dwordx4 v[8:9], v[60:63], off offset:384
	global_store_dwordx4 v[8:9], v[64:67], off offset:448
	global_load_dwordx4 v[150:153], v[6:7], off offset:1792
	global_load_dwordx4 v[154:157], v[6:7], off offset:1808
	global_load_dwordx4 v[158:161], v[6:7], off offset:1920
	global_load_dwordx4 v[162:165], v[6:7], off offset:1936
	ds_read_b128 v[36:39], v10 offset:1280
	ds_read_b128 v[40:43], v10 offset:1296
	ds_read_b128 v[44:47], v10 offset:1408
	ds_read_b128 v[48:51], v10 offset:1424
	s_waitcnt vmcnt(18)
	s_waitcnt lgkmcnt(4)
	v_mfma_f32_16x16x4_f32 v[12:15], v98, v20, v[12:15]
	v_mfma_f32_16x16x4_f32 v[16:19], v99, v21, v[16:19]
	v_cvt_pk_bf16_f32 v52, v98, v99
	v_mfma_f32_16x16x4_f32 v[12:15], v100, v22, v[12:15]
	v_mfma_f32_16x16x4_f32 v[16:19], v101, v23, v[16:19]
	v_cvt_pk_bf16_f32 v53, v100, v101
	v_mfma_f32_16x16x4_f32 v[12:15], v102, v24, v[12:15]
	v_mfma_f32_16x16x4_f32 v[16:19], v103, v25, v[16:19]
	v_cvt_pk_bf16_f32 v54, v102, v103
	v_mfma_f32_16x16x4_f32 v[12:15], v104, v26, v[12:15]
	v_mfma_f32_16x16x4_f32 v[16:19], v105, v27, v[16:19]
	v_cvt_pk_bf16_f32 v55, v104, v105
	v_mfma_f32_16x16x4_f32 v[12:15], v106, v28, v[12:15]
	v_mfma_f32_16x16x4_f32 v[16:19], v107, v29, v[16:19]
	v_cvt_pk_bf16_f32 v56, v106, v107
	v_mfma_f32_16x16x4_f32 v[12:15], v108, v30, v[12:15]
	v_mfma_f32_16x16x4_f32 v[16:19], v109, v31, v[16:19]
	v_cvt_pk_bf16_f32 v57, v108, v109
	v_mfma_f32_16x16x4_f32 v[12:15], v110, v32, v[12:15]
	v_mfma_f32_16x16x4_f32 v[16:19], v111, v33, v[16:19]
	v_cvt_pk_bf16_f32 v58, v110, v111
	v_mfma_f32_16x16x4_f32 v[12:15], v112, v34, v[12:15]
	v_mfma_f32_16x16x4_f32 v[16:19], v113, v35, v[16:19]
	v_cvt_pk_bf16_f32 v59, v112, v113
	global_store_dwordx4 v[8:9], v[52:55], off offset:512
	global_store_dwordx4 v[8:9], v[56:59], off offset:576
	global_load_dwordx4 v[98:101], v[6:7], off offset:2048
	global_load_dwordx4 v[102:105], v[6:7], off offset:2064
	global_load_dwordx4 v[106:109], v[6:7], off offset:2176
	global_load_dwordx4 v[110:113], v[6:7], off offset:2192
	ds_read_b128 v[20:23], v10 offset:1536
	ds_read_b128 v[24:27], v10 offset:1552
	ds_read_b128 v[28:31], v10 offset:1664
	ds_read_b128 v[32:35], v10 offset:1680
	s_waitcnt vmcnt(18)
	s_waitcnt lgkmcnt(4)
; DI_ unsigned pk2(float lo, float hi) { typedef float f2 __attribute__((ext_vector_type(2))); typedef __bf16 b2 __attribute__((ext_vector_type(2))); f2 v = {lo, hi}; b2 b = __builtin_convertvector(v, b2); return __builtin_bit_cast(unsigned, b); }
; template <int NS, bool LN, bool WF32, bool WBF, int SKMODE>
; DI_ void row_pass(const float* Xin, float* Xout, bf16_t* XBo, const float* g, const float* b, const float* WsT, float* sk_out, const float* sk_bias, int row0, int nrows, int gw, int NGW, int lane) {
;     ...
;         if (WBF) {
;             u32x2* xo = (u32x2*)(XBo + (size_t)row * D) + lane;
; #pragma unroll
;             for (int j = 0; j < 4; ++j) { u32x2 w; w.x = pk2(v[j][0], v[j][1]); w.y = pk2(v[j][2], v[j][3]); xo[64 * j] = w; }
;         }
;         if (NS > 0) {
; #pragma unroll 1
;             for (int grp = 0; grp < NS / 8; ++grp) {
;                 float a[8];
; #pragma unroll
;                 for (int jc = 0; jc < 8; ++jc) {
;                     float s = 0.f;
; #pragma unroll
;                     for (int j = 0; j < 4; ++j) { const f32x4 w = *(const f32x4*)(WsT + (8 * grp + jc) * WST + 4 * (lane + 64 * j)); s += (v[j][0] * w[0] + v[j][1] * w[1]) + (v[j][2] * w[2] + v[j][3] * w[3]); }
	v_mfma_f32_16x16x4_f32 v[12:15], v114, v36, v[12:15]
	v_mfma_f32_16x16x4_f32 v[16:19], v115, v37, v[16:19]
	v_cvt_pk_bf16_f32 v60, v114, v115
	v_mfma_f32_16x16x4_f32 v[12:15], v116, v38, v[12:15]
	v_mfma_f32_16x16x4_f32 v[16:19], v117, v39, v[16:19]
	v_cvt_pk_bf16_f32 v61, v116, v117
	v_mfma_f32_16x16x4_f32 v[12:15], v118, v40, v[12:15]
	v_mfma_f32_16x16x4_f32 v[16:19], v119, v41, v[16:19]
	v_cvt_pk_bf16_f32 v62, v118, v119
	v_mfma_f32_16x16x4_f32 v[12:15], v120, v42, v[12:15]
	v_mfma_f32_16x16x4_f32 v[16:19], v121, v43, v[16:19]
	v_cvt_pk_bf16_f32 v63, v120, v121
	v_mfma_f32_16x16x4_f32 v[12:15], v122, v44, v[12:15]
	v_mfma_f32_16x16x4_f32 v[16:19], v123, v45, v[16:19]
	v_cvt_pk_bf16_f32 v64, v122, v123
	v_mfma_f32_16x16x4_f32 v[12:15], v124, v46, v[12:15]
	v_mfma_f32_16x16x4_f32 v[16:19], v125, v47, v[16:19]
	v_cvt_pk_bf16_f32 v65, v124, v125
	v_mfma_f32_16x16x4_f32 v[12:15], v126, v48, v[12:15]
	v_mfma_f32_16x16x4_f32 v[16:19], v127, v49, v[16:19]
	v_cvt_pk_bf16_f32 v66, v126, v127
	v_mfma_f32_16x16x4_f32 v[12:15], v128, v50, v[12:15]
	v_mfma_f32_16x16x4_f32 v[16:19], v129, v51, v[16:19]
	v_cvt_pk_bf16_f32 v67, v128, v129
	global_store_dwordx4 v[8:9], v[60:63], off offset:640
	global_store_dwordx4 v[8:9], v[64:67], off offset:704
	global_load_dwordx4 v[114:117], v[6:7], off offset:2304
	global_load_dwordx4 v[118:121], v[6:7], off offset:2320
	global_load_dwordx4 v[122:125], v[6:7], off offset:2432
	global_load_dwordx4 v[126:129], v[6:7], off offset:2448
	ds_read_b128 v[36:39], v10 offset:1792
	ds_read_b128 v[40:43], v10 offset:1808
	ds_read_b128 v[44:47], v10 offset:1920
	ds_read_b128 v[48:51], v10 offset:1936
	s_waitcnt vmcnt(18)
	s_waitcnt lgkmcnt(4)
	v_mfma_f32_16x16x4_f32 v[12:15], v130, v20, v[12:15]
	v_mfma_f32_16x16x4_f32 v[16:19], v131, v21, v[16:19]
	v_cvt_pk_bf16_f32 v52, v130, v131
	v_mfma_f32_16x16x4_f32 v[12:15], v132, v22, v[12:15]
	v_mfma_f32_16x16x4_f32 v[16:19], v133, v23, v[16:19]
	v_cvt_pk_bf16_f32 v53, v132, v133
	v_mfma_f32_16x16x4_f32 v[12:15], v134, v24, v[12:15]
	v_mfma_f32_16x16x4_f32 v[16:19], v135, v25, v[16:19]
	v_cvt_pk_bf16_f32 v54, v134, v135
	v_mfma_f32_16x16x4_f32 v[12:15], v136, v26, v[12:15]
	v_mfma_f32_16x16x4_f32 v[16:19], v137, v27, v[16:19]
	v_cvt_pk_bf16_f32 v55, v136, v137
	v_mfma_f32_16x16x4_f32 v[12:15], v138, v28, v[12:15]
	v_mfma_f32_16x16x4_f32 v[16:19], v139, v29, v[16:19]
	v_cvt_pk_bf16_f32 v56, v138, v139
	v_mfma_f32_16x16x4_f32 v[12:15], v140, v30, v[12:15]
	v_mfma_f32_16x16x4_f32 v[16:19], v141, v31, v[16:19]
	v_cvt_pk_bf16_f32 v57, v140, v141
	v_mfma_f32_16x16x4_f32 v[12:15], v142, v32, v[12:15]
	v_mfma_f32_16x16x4_f32 v[16:19], v143, v33, v[16:19]
	v_cvt_pk_bf16_f32 v58, v142, v143
	v_mfma_f32_16x16x4_f32 v[12:15], v144, v34, v[12:15]
	v_mfma_f32_16x16x4_f32 v[16:19], v145, v35, v[16:19]
	v_cvt_pk_bf16_f32 v59, v144, v145
	global_store_dwordx4 v[8:9], v[52:55], off offset:768
	global_store_dwordx4 v[8:9], v[56:59], off offset:832
	global_load_dwordx4 v[130:133], v[6:7], off offset:2560
	global_load_dwordx4 v[134:137], v[6:7], off offset:2576
	global_load_dwordx4 v[138:141], v[6:7], off offset:2688
	global_load_dwordx4 v[142:145], v[6:7], off offset:2704
	ds_read_b128 v[20:23], v10 offset:2048
	ds_read_b128 v[24:27], v10 offset:2064
	ds_read_b128 v[28:31], v10 offset:2176
	ds_read_b128 v[32:35], v10 offset:2192
	s_waitcnt vmcnt(18)
	s_waitcnt lgkmcnt(4)
	v_mfma_f32_16x16x4_f32 v[12:15], v150, v36, v[12:15]
	v_mfma_f32_16x16x4_f32 v[16:19], v151, v37, v[16:19]
	v_cvt_pk_bf16_f32 v60, v150, v151
	v_mfma_f32_16x16x4_f32 v[12:15], v152, v38, v[12:15]
	v_mfma_f32_16x16x4_f32 v[16:19], v153, v39, v[16:19]
	v_cvt_pk_bf16_f32 v61, v152, v153
	v_mfma_f32_16x16x4_f32 v[12:15], v154, v40, v[12:15]
	v_mfma_f32_16x16x4_f32 v[16:19], v155, v41, v[16:19]
	v_cvt_pk_bf16_f32 v62, v154, v155
	v_mfma_f32_16x16x4_f32 v[12:15], v156, v42, v[12:15]
	v_mfma_f32_16x16x4_f32 v[16:19], v157, v43, v[16:19]
	v_cvt_pk_bf16_f32 v63, v156, v157
	v_mfma_f32_16x16x4_f32 v[12:15], v158, v44, v[12:15]
	v_mfma_f32_16x16x4_f32 v[16:19], v159, v45, v[16:19]
	v_cvt_pk_bf16_f32 v64, v158, v159
	v_mfma_f32_16x16x4_f32 v[12:15], v160, v46, v[12:15]
	v_mfma_f32_16x16x4_f32 v[16:19], v161, v47, v[16:19]
	v_cvt_pk_bf16_f32 v65, v160, v161
	v_mfma_f32_16x16x4_f32 v[12:15], v162, v48, v[12:15]
	v_mfma_f32_16x16x4_f32 v[16:19], v163, v49, v[16:19]
	v_cvt_pk_bf16_f32 v66, v162, v163
	v_mfma_f32_16x16x4_f32 v[12:15], v164, v50, v[12:15]
	v_mfma_f32_16x16x4_f32 v[16:19], v165, v51, v[16:19]
	v_cvt_pk_bf16_f32 v67, v164, v165
	global_store_dwordx4 v[8:9], v[60:63], off offset:896
	global_store_dwordx4 v[8:9], v[64:67], off offset:960
	global_load_dwordx4 v[150:153], v[6:7], off offset:2816
	global_load_dwordx4 v[154:157], v[6:7], off offset:2832
	global_load_dwordx4 v[158:161], v[6:7], off offset:2944
	global_load_dwordx4 v[162:165], v[6:7], off offset:2960
	ds_read_b128 v[36:39], v10 offset:2304
	ds_read_b128 v[40:43], v10 offset:2320
	ds_read_b128 v[44:47], v10 offset:2432
	ds_read_b128 v[48:51], v10 offset:2448
	s_waitcnt vmcnt(18)
	s_waitcnt lgkmcnt(4)
; DI_ unsigned pk2(float lo, float hi) { typedef float f2 __attribute__((ext_vector_type(2))); typedef __bf16 b2 __attribute__((ext_vector_type(2))); f2 v = {lo, hi}; b2 b = __builtin_convertvector(v, b2); return __builtin_bit_cast(unsigned, b); }
; template <int NS, bool LN, bool WF32, bool WBF, int SKMODE>
; DI_ void row_pass(const float* Xin, float* Xout, bf16_t* XBo, const float* g, const float* b, const float* WsT, float* sk_out, const float* sk_bias, int row0, int nrows, int gw, int NGW, int lane) {
;     ...
;         if (WBF) {
;             u32x2* xo = (u32x2*)(XBo + (size_t)row * D) + lane;
; #pragma unroll
;             for (int j = 0; j < 4; ++j) { u32x2 w; w.x = pk2(v[j][0], v[j][1]); w.y = pk2(v[j][2], v[j][3]); xo[64 * j] = w; }
;         }
;         if (NS > 0) {
; #pragma unroll 1
;             for (int grp = 0; grp < NS / 8; ++grp) {
;                 float a[8];
; #pragma unroll
;                 for (int jc = 0; jc < 8; ++jc) {
;                     float s = 0.f;
; #pragma unroll
;                     for (int j = 0; j < 4; ++j) { const f32x4 w = *(const f32x4*)(WsT + (8 * grp + jc) * WST + 4 * (lane + 64 * j)); s += (v[j][0] * w[0] + v[j][1] * w[1]) + (v[j][2] * w[2] + v[j][3] * w[3]); }
	v_mfma_f32_16x16x4_f32 v[12:15], v98, v20, v[12:15]
	v_mfma_f32_16x16x4_f32 v[16:19], v99, v21, v[16:19]
	v_cvt_pk_bf16_f32 v52, v98, v99
	v_mfma_f32_16x16x4_f32 v[12:15], v100, v22, v[12:15]
	v_mfma_f32_16x16x4_f32 v[16:19], v101, v23, v[16:19]
	v_cvt_pk_bf16_f32 v53, v100, v101
	v_mfma_f32_16x16x4_f32 v[12:15], v102, v24, v[12:15]
	v_mfma_f32_16x16x4_f32 v[16:19], v103, v25, v[16:19]
	v_cvt_pk_bf16_f32 v54, v102, v103
	v_mfma_f32_16x16x4_f32 v[12:15], v104, v26, v[12:15]
	v_mfma_f32_16x16x4_f32 v[16:19], v105, v27, v[16:19]
	v_cvt_pk_bf16_f32 v55, v104, v105
	v_mfma_f32_16x16x4_f32 v[12:15], v106, v28, v[12:15]
	v_mfma_f32_16x16x4_f32 v[16:19], v107, v29, v[16:19]
	v_cvt_pk_bf16_f32 v56, v106, v107
	v_mfma_f32_16x16x4_f32 v[12:15], v108, v30, v[12:15]
	v_mfma_f32_16x16x4_f32 v[16:19], v109, v31, v[16:19]
	v_cvt_pk_bf16_f32 v57, v108, v109
	v_mfma_f32_16x16x4_f32 v[12:15], v110, v32, v[12:15]
	v_mfma_f32_16x16x4_f32 v[16:19], v111, v33, v[16:19]
	v_cvt_pk_bf16_f32 v58, v110, v111
	v_mfma_f32_16x16x4_f32 v[12:15], v112, v34, v[12:15]
	v_mfma_f32_16x16x4_f32 v[16:19], v113, v35, v[16:19]
	v_cvt_pk_bf16_f32 v59, v112, v113
	global_store_dwordx4 v[8:9], v[52:55], off offset:1024
	global_store_dwordx4 v[8:9], v[56:59], off offset:1088
	global_load_dwordx4 v[98:101], v[6:7], off offset:3072
	global_load_dwordx4 v[102:105], v[6:7], off offset:3088
	global_load_dwordx4 v[106:109], v[6:7], off offset:3200
	global_load_dwordx4 v[110:113], v[6:7], off offset:3216
	ds_read_b128 v[20:23], v10 offset:2560
	ds_read_b128 v[24:27], v10 offset:2576
	ds_read_b128 v[28:31], v10 offset:2688
	ds_read_b128 v[32:35], v10 offset:2704
	s_waitcnt vmcnt(18)
	s_waitcnt lgkmcnt(4)
	v_mfma_f32_16x16x4_f32 v[12:15], v114, v36, v[12:15]
	v_mfma_f32_16x16x4_f32 v[16:19], v115, v37, v[16:19]
	v_cvt_pk_bf16_f32 v60, v114, v115
	v_mfma_f32_16x16x4_f32 v[12:15], v116, v38, v[12:15]
	v_mfma_f32_16x16x4_f32 v[16:19], v117, v39, v[16:19]
	v_cvt_pk_bf16_f32 v61, v116, v117
	v_mfma_f32_16x16x4_f32 v[12:15], v118, v40, v[12:15]
	v_mfma_f32_16x16x4_f32 v[16:19], v119, v41, v[16:19]
	v_cvt_pk_bf16_f32 v62, v118, v119
	v_mfma_f32_16x16x4_f32 v[12:15], v120, v42, v[12:15]
	v_mfma_f32_16x16x4_f32 v[16:19], v121, v43, v[16:19]
	v_cvt_pk_bf16_f32 v63, v120, v121
	v_mfma_f32_16x16x4_f32 v[12:15], v122, v44, v[12:15]
	v_mfma_f32_16x16x4_f32 v[16:19], v123, v45, v[16:19]
	v_cvt_pk_bf16_f32 v64, v122, v123
	v_mfma_f32_16x16x4_f32 v[12:15], v124, v46, v[12:15]
	v_mfma_f32_16x16x4_f32 v[16:19], v125, v47, v[16:19]
	v_cvt_pk_bf16_f32 v65, v124, v125
	v_mfma_f32_16x16x4_f32 v[12:15], v126, v48, v[12:15]
	v_mfma_f32_16x16x4_f32 v[16:19], v127, v49, v[16:19]
	v_cvt_pk_bf16_f32 v66, v126, v127
	v_mfma_f32_16x16x4_f32 v[12:15], v128, v50, v[12:15]
	v_mfma_f32_16x16x4_f32 v[16:19], v129, v51, v[16:19]
	v_cvt_pk_bf16_f32 v67, v128, v129
	global_store_dwordx4 v[8:9], v[60:63], off offset:1152
	global_store_dwordx4 v[8:9], v[64:67], off offset:1216
	global_load_dwordx4 v[114:117], v[6:7], off offset:3328
	global_load_dwordx4 v[118:121], v[6:7], off offset:3344
	global_load_dwordx4 v[122:125], v[6:7], off offset:3456
	global_load_dwordx4 v[126:129], v[6:7], off offset:3472
	ds_read_b128 v[36:39], v10 offset:2816
	ds_read_b128 v[40:43], v10 offset:2832
	ds_read_b128 v[44:47], v10 offset:2944
	ds_read_b128 v[48:51], v10 offset:2960
	s_waitcnt vmcnt(18)
	s_waitcnt lgkmcnt(4)
	v_mfma_f32_16x16x4_f32 v[12:15], v130, v20, v[12:15]
	v_mfma_f32_16x16x4_f32 v[16:19], v131, v21, v[16:19]
	v_cvt_pk_bf16_f32 v52, v130, v131
	v_mfma_f32_16x16x4_f32 v[12:15], v132, v22, v[12:15]
	v_mfma_f32_16x16x4_f32 v[16:19], v133, v23, v[16:19]
	v_cvt_pk_bf16_f32 v53, v132, v133
	v_mfma_f32_16x16x4_f32 v[12:15], v134, v24, v[12:15]
	v_mfma_f32_16x16x4_f32 v[16:19], v135, v25, v[16:19]
	v_cvt_pk_bf16_f32 v54, v134, v135
	v_mfma_f32_16x16x4_f32 v[12:15], v136, v26, v[12:15]
	v_mfma_f32_16x16x4_f32 v[16:19], v137, v27, v[16:19]
	v_cvt_pk_bf16_f32 v55, v136, v137
	v_mfma_f32_16x16x4_f32 v[12:15], v138, v28, v[12:15]
	v_mfma_f32_16x16x4_f32 v[16:19], v139, v29, v[16:19]
	v_cvt_pk_bf16_f32 v56, v138, v139
	v_mfma_f32_16x16x4_f32 v[12:15], v140, v30, v[12:15]
	v_mfma_f32_16x16x4_f32 v[16:19], v141, v31, v[16:19]
	v_cvt_pk_bf16_f32 v57, v140, v141
	v_mfma_f32_16x16x4_f32 v[12:15], v142, v32, v[12:15]
	v_mfma_f32_16x16x4_f32 v[16:19], v143, v33, v[16:19]
	v_cvt_pk_bf16_f32 v58, v142, v143
	v_mfma_f32_16x16x4_f32 v[12:15], v144, v34, v[12:15]
	v_mfma_f32_16x16x4_f32 v[16:19], v145, v35, v[16:19]
	v_cvt_pk_bf16_f32 v59, v144, v145
	global_store_dwordx4 v[8:9], v[52:55], off offset:1280
	global_store_dwordx4 v[8:9], v[56:59], off offset:1344
	global_load_dwordx4 v[130:133], v[6:7], off offset:3584
	global_load_dwordx4 v[134:137], v[6:7], off offset:3600
	global_load_dwordx4 v[138:141], v[6:7], off offset:3712
	global_load_dwordx4 v[142:145], v[6:7], off offset:3728
	ds_read_b128 v[20:23], v10 offset:3072
	ds_read_b128 v[24:27], v10 offset:3088
	ds_read_b128 v[28:31], v10 offset:3200
	ds_read_b128 v[32:35], v10 offset:3216
	s_waitcnt vmcnt(18)
	s_waitcnt lgkmcnt(4)
; DI_ unsigned pk2(float lo, float hi) { typedef float f2 __attribute__((ext_vector_type(2))); typedef __bf16 b2 __attribute__((ext_vector_type(2))); f2 v = {lo, hi}; b2 b = __builtin_convertvector(v, b2); return __builtin_bit_cast(unsigned, b); }
; template <int NS, bool LN, bool WF32, bool WBF, int SKMODE>
; DI_ void row_pass(const float* Xin, float* Xout, bf16_t* XBo, const float* g, const float* b, const float* WsT, float* sk_out, const float* sk_bias, int row0, int nrows, int gw, int NGW, int lane) {
;     ...
;         if (WBF) {
;             u32x2* xo = (u32x2*)(XBo + (size_t)row * D) + lane;
; #pragma unroll
;             for (int j = 0; j < 4; ++j) { u32x2 w; w.x = pk2(v[j][0], v[j][1]); w.y = pk2(v[j][2], v[j][3]); xo[64 * j] = w; }
;         }
;         if (NS > 0) {
; #pragma unroll 1
;             for (int grp = 0; grp < NS / 8; ++grp) {
;                 float a[8];
; #pragma unroll
;                 for (int jc = 0; jc < 8; ++jc) {
;                     float s = 0.f;
; #pragma unroll
;                     for (int j = 0; j < 4; ++j) { const f32x4 w = *(const f32x4*)(WsT + (8 * grp + jc) * WST + 4 * (lane + 64 * j)); s += (v[j][0] * w[0] + v[j][1] * w[1]) + (v[j][2] * w[2] + v[j][3] * w[3]); }
	v_mfma_f32_16x16x4_f32 v[12:15], v150, v36, v[12:15]
	v_mfma_f32_16x16x4_f32 v[16:19], v151, v37, v[16:19]
	v_cvt_pk_bf16_f32 v60, v150, v151
	v_mfma_f32_16x16x4_f32 v[12:15], v152, v38, v[12:15]
	v_mfma_f32_16x16x4_f32 v[16:19], v153, v39, v[16:19]
	v_cvt_pk_bf16_f32 v61, v152, v153
	v_mfma_f32_16x16x4_f32 v[12:15], v154, v40, v[12:15]
	v_mfma_f32_16x16x4_f32 v[16:19], v155, v41, v[16:19]
	v_cvt_pk_bf16_f32 v62, v154, v155
	v_mfma_f32_16x16x4_f32 v[12:15], v156, v42, v[12:15]
	v_mfma_f32_16x16x4_f32 v[16:19], v157, v43, v[16:19]
	v_cvt_pk_bf16_f32 v63, v156, v157
	v_mfma_f32_16x16x4_f32 v[12:15], v158, v44, v[12:15]
	v_mfma_f32_16x16x4_f32 v[16:19], v159, v45, v[16:19]
	v_cvt_pk_bf16_f32 v64, v158, v159
	v_mfma_f32_16x16x4_f32 v[12:15], v160, v46, v[12:15]
	v_mfma_f32_16x16x4_f32 v[16:19], v161, v47, v[16:19]
	v_cvt_pk_bf16_f32 v65, v160, v161
	v_mfma_f32_16x16x4_f32 v[12:15], v162, v48, v[12:15]
	v_mfma_f32_16x16x4_f32 v[16:19], v163, v49, v[16:19]
	v_cvt_pk_bf16_f32 v66, v162, v163
	v_mfma_f32_16x16x4_f32 v[12:15], v164, v50, v[12:15]
	v_mfma_f32_16x16x4_f32 v[16:19], v165, v51, v[16:19]
	v_cvt_pk_bf16_f32 v67, v164, v165
	global_store_dwordx4 v[8:9], v[60:63], off offset:1408
	global_store_dwordx4 v[8:9], v[64:67], off offset:1472
	global_load_dwordx4 v[150:153], v[6:7], off offset:3840
	global_load_dwordx4 v[154:157], v[6:7], off offset:3856
	global_load_dwordx4 v[158:161], v[6:7], off offset:3968
	global_load_dwordx4 v[162:165], v[6:7], off offset:3984
	ds_read_b128 v[36:39], v10 offset:3328
	ds_read_b128 v[40:43], v10 offset:3344
	ds_read_b128 v[44:47], v10 offset:3456
	ds_read_b128 v[48:51], v10 offset:3472
	s_waitcnt vmcnt(18)
	s_waitcnt lgkmcnt(4)
	v_mfma_f32_16x16x4_f32 v[12:15], v98, v20, v[12:15]
	v_mfma_f32_16x16x4_f32 v[16:19], v99, v21, v[16:19]
	v_cvt_pk_bf16_f32 v52, v98, v99
	v_mfma_f32_16x16x4_f32 v[12:15], v100, v22, v[12:15]
	v_mfma_f32_16x16x4_f32 v[16:19], v101, v23, v[16:19]
	v_cvt_pk_bf16_f32 v53, v100, v101
	v_mfma_f32_16x16x4_f32 v[12:15], v102, v24, v[12:15]
	v_mfma_f32_16x16x4_f32 v[16:19], v103, v25, v[16:19]
	v_cvt_pk_bf16_f32 v54, v102, v103
	v_mfma_f32_16x16x4_f32 v[12:15], v104, v26, v[12:15]
	v_mfma_f32_16x16x4_f32 v[16:19], v105, v27, v[16:19]
	v_cvt_pk_bf16_f32 v55, v104, v105
	v_mfma_f32_16x16x4_f32 v[12:15], v106, v28, v[12:15]
	v_mfma_f32_16x16x4_f32 v[16:19], v107, v29, v[16:19]
	v_cvt_pk_bf16_f32 v56, v106, v107
	v_mfma_f32_16x16x4_f32 v[12:15], v108, v30, v[12:15]
	v_mfma_f32_16x16x4_f32 v[16:19], v109, v31, v[16:19]
	v_cvt_pk_bf16_f32 v57, v108, v109
	v_mfma_f32_16x16x4_f32 v[12:15], v110, v32, v[12:15]
	v_mfma_f32_16x16x4_f32 v[16:19], v111, v33, v[16:19]
	v_cvt_pk_bf16_f32 v58, v110, v111
	v_mfma_f32_16x16x4_f32 v[12:15], v112, v34, v[12:15]
	v_mfma_f32_16x16x4_f32 v[16:19], v113, v35, v[16:19]
	v_cvt_pk_bf16_f32 v59, v112, v113
	global_store_dwordx4 v[8:9], v[52:55], off offset:1536
	global_store_dwordx4 v[8:9], v[56:59], off offset:1600
	ds_read_b128 v[20:23], v10 offset:3584
	ds_read_b128 v[24:27], v10 offset:3600
	ds_read_b128 v[28:31], v10 offset:3712
	ds_read_b128 v[32:35], v10 offset:3728
	s_waitcnt vmcnt(14)
	s_waitcnt lgkmcnt(4)
	v_mfma_f32_16x16x4_f32 v[12:15], v114, v36, v[12:15]
	v_mfma_f32_16x16x4_f32 v[16:19], v115, v37, v[16:19]
	v_cvt_pk_bf16_f32 v60, v114, v115
	v_mfma_f32_16x16x4_f32 v[12:15], v116, v38, v[12:15]
	v_mfma_f32_16x16x4_f32 v[16:19], v117, v39, v[16:19]
	v_cvt_pk_bf16_f32 v61, v116, v117
	v_mfma_f32_16x16x4_f32 v[12:15], v118, v40, v[12:15]
	v_mfma_f32_16x16x4_f32 v[16:19], v119, v41, v[16:19]
	v_cvt_pk_bf16_f32 v62, v118, v119
	v_mfma_f32_16x16x4_f32 v[12:15], v120, v42, v[12:15]
	v_mfma_f32_16x16x4_f32 v[16:19], v121, v43, v[16:19]
	v_cvt_pk_bf16_f32 v63, v120, v121
	v_mfma_f32_16x16x4_f32 v[12:15], v122, v44, v[12:15]
	v_mfma_f32_16x16x4_f32 v[16:19], v123, v45, v[16:19]
	v_cvt_pk_bf16_f32 v64, v122, v123
	v_mfma_f32_16x16x4_f32 v[12:15], v124, v46, v[12:15]
	v_mfma_f32_16x16x4_f32 v[16:19], v125, v47, v[16:19]
	v_cvt_pk_bf16_f32 v65, v124, v125
	v_mfma_f32_16x16x4_f32 v[12:15], v126, v48, v[12:15]
	v_mfma_f32_16x16x4_f32 v[16:19], v127, v49, v[16:19]
	v_cvt_pk_bf16_f32 v66, v126, v127
	v_mfma_f32_16x16x4_f32 v[12:15], v128, v50, v[12:15]
	v_mfma_f32_16x16x4_f32 v[16:19], v129, v51, v[16:19]
	v_cvt_pk_bf16_f32 v67, v128, v129
	global_store_dwordx4 v[8:9], v[60:63], off offset:1664
	global_store_dwordx4 v[8:9], v[64:67], off offset:1728
	ds_read_b128 v[36:39], v10 offset:3840
	ds_read_b128 v[40:43], v10 offset:3856
	ds_read_b128 v[44:47], v10 offset:3968
	ds_read_b128 v[48:51], v10 offset:3984
	s_waitcnt vmcnt(10)
	s_waitcnt lgkmcnt(4)
	v_mfma_f32_16x16x4_f32 v[12:15], v130, v20, v[12:15]
	v_mfma_f32_16x16x4_f32 v[16:19], v131, v21, v[16:19]
	v_cvt_pk_bf16_f32 v52, v130, v131
	v_mfma_f32_16x16x4_f32 v[12:15], v132, v22, v[12:15]
	v_mfma_f32_16x16x4_f32 v[16:19], v133, v23, v[16:19]
	v_cvt_pk_bf16_f32 v53, v132, v133
	v_mfma_f32_16x16x4_f32 v[12:15], v134, v24, v[12:15]
	v_mfma_f32_16x16x4_f32 v[16:19], v135, v25, v[16:19]
	v_cvt_pk_bf16_f32 v54, v134, v135
	v_mfma_f32_16x16x4_f32 v[12:15], v136, v26, v[12:15]
	v_mfma_f32_16x16x4_f32 v[16:19], v137, v27, v[16:19]
	v_cvt_pk_bf16_f32 v55, v136, v137
	v_mfma_f32_16x16x4_f32 v[12:15], v138, v28, v[12:15]
	v_mfma_f32_16x16x4_f32 v[16:19], v139, v29, v[16:19]
	v_cvt_pk_bf16_f32 v56, v138, v139
	v_mfma_f32_16x16x4_f32 v[12:15], v140, v30, v[12:15]
	v_mfma_f32_16x16x4_f32 v[16:19], v141, v31, v[16:19]
	v_cvt_pk_bf16_f32 v57, v140, v141
	v_mfma_f32_16x16x4_f32 v[12:15], v142, v32, v[12:15]
	v_mfma_f32_16x16x4_f32 v[16:19], v143, v33, v[16:19]
	v_cvt_pk_bf16_f32 v58, v142, v143
	v_mfma_f32_16x16x4_f32 v[12:15], v144, v34, v[12:15]
	v_mfma_f32_16x16x4_f32 v[16:19], v145, v35, v[16:19]
	v_cvt_pk_bf16_f32 v59, v144, v145
	global_store_dwordx4 v[8:9], v[52:55], off offset:1792
	global_store_dwordx4 v[8:9], v[56:59], off offset:1856
	s_waitcnt vmcnt(6)
; DI_ float log_sigmoid(float v) { return fminf(v, 0.f) - log1pf(expf(-fabsf(v))); }
; template <int NS, bool LN, bool WF32, bool WBF, int SKMODE>
; DI_ void row_pass(const float* Xin, float* Xout, bf16_t* XBo, const float* g, const float* b, const float* WsT, float* sk_out, const float* sk_bias, int row0, int nrows, int gw, int NGW, int lane) {
;     ...
;                     for (int j = 0; j < 4; ++j) { const f32x4 w = *(const f32x4*)(WsT + (8 * grp + jc) * WST + 4 * (lane + 64 * j)); s += (v[j][0] * w[0] + v[j][1] * w[1]) + (v[j][2] * w[2] + v[j][3] * w[3]); }
;                     a[jc] = s;
;                 }
;                 { const bool up = (lane & 32) != 0;
; #pragma unroll
;                   for (int i = 0; i < 4; ++i) { const float send = up ? a[i] : a[4 + i], keep = up ? a[4 + i] : a[i]; a[i] = keep + __shfl_xor(send, 32); } }
;                 { const bool up = (lane & 16) != 0;
; #pragma unroll
;                   for (int i = 0; i < 2; ++i) { const float send = up ? a[i] : a[2 + i], keep = up ? a[2 + i] : a[i]; a[i] = keep + __shfl_xor(send, 16); } }
;                 { const bool up = (lane & 8) != 0; const float send = up ? a[0] : a[1], keep = up ? a[1] : a[0]; a[0] = keep + __shfl_xor(send, 8); }
;                 a[0] += __shfl_xor(a[0], 4); a[0] += __shfl_xor(a[0], 2); a[0] += __shfl_xor(a[0], 1);
;                 const int jo = 8 * grp + (lane >> 3);
;                 if ((lane & 7) == 0) sk_out[(size_t)row * NS + jo] = (SKMODE == 1) ? log_sigmoid(a[0] + sk_bias[jo]) : a[0];
	s_waitcnt lgkmcnt(0)
	v_mfma_f32_16x16x4_f32 v[12:15], v150, v36, v[12:15]
	v_mfma_f32_16x16x4_f32 v[16:19], v151, v37, v[16:19]
	v_cvt_pk_bf16_f32 v60, v150, v151
	v_mfma_f32_16x16x4_f32 v[12:15], v152, v38, v[12:15]
	v_mfma_f32_16x16x4_f32 v[16:19], v153, v39, v[16:19]
	v_cvt_pk_bf16_f32 v61, v152, v153
	v_mfma_f32_16x16x4_f32 v[12:15], v154, v40, v[12:15]
	v_mfma_f32_16x16x4_f32 v[16:19], v155, v41, v[16:19]
	v_cvt_pk_bf16_f32 v62, v154, v155
	v_mfma_f32_16x16x4_f32 v[12:15], v156, v42, v[12:15]
	v_mfma_f32_16x16x4_f32 v[16:19], v157, v43, v[16:19]
	v_cvt_pk_bf16_f32 v63, v156, v157
	v_mfma_f32_16x16x4_f32 v[12:15], v158, v44, v[12:15]
	v_mfma_f32_16x16x4_f32 v[16:19], v159, v45, v[16:19]
	v_cvt_pk_bf16_f32 v64, v158, v159
	v_mfma_f32_16x16x4_f32 v[12:15], v160, v46, v[12:15]
	v_mfma_f32_16x16x4_f32 v[16:19], v161, v47, v[16:19]
	v_cvt_pk_bf16_f32 v65, v160, v161
	v_mfma_f32_16x16x4_f32 v[12:15], v162, v48, v[12:15]
	v_mfma_f32_16x16x4_f32 v[16:19], v163, v49, v[16:19]
	v_cvt_pk_bf16_f32 v66, v162, v163
	v_mfma_f32_16x16x4_f32 v[12:15], v164, v50, v[12:15]
	v_mfma_f32_16x16x4_f32 v[16:19], v165, v51, v[16:19]
	v_cvt_pk_bf16_f32 v67, v164, v165
	global_store_dwordx4 v[8:9], v[60:63], off offset:1920
	global_store_dwordx4 v[8:9], v[64:67], off offset:1984
	s_nop 15
	v_add_f32_e32 v12, v12, v16
	v_add_f32_e32 v13, v13, v17
	v_add_f32_e32 v14, v14, v18
	v_add_f32_e32 v15, v15, v19
	v_lshl_add_u32 v22, v3, 2, s0
	v_lshlrev_b32_e32 v22, 6, v22
	v_lshl_add_u32 v22, v2, 2, v22
	v_mov_b32_e32 v23, 0
	v_mov_b32_e32 v4, s3
	v_mov_b32_e32 v5, s33
	v_lshl_add_u64 v[22:23], v[4:5], 0, v[22:23]
	global_load_dword v24, v11, s[62:63]
	s_mov_b32 s28, 0xbfb8aa3b
	s_mov_b32 s29, 0xb2a5705f
	s_mov_b32 s30, 0x42ce8ed0
	s_mov_b32 s31, 0xc2b17218
	s_mov_b32 s34, 0x7f800000
	s_mov_b32 s35, 0x3f2aaaab
	s_mov_b32 s36, 0x3f317218
	s_mov_b32 s37, 0x33800000
	v_mov_b32_e32 v49, 0x3ecc95a3
	v_mov_b32_e32 v50, 0x7f800000
	v_mov_b32_e32 v40, 0x3f317218
	s_waitcnt vmcnt(0)
	v_add_f32_e32 v34, v12, v24
	v_mul_f32_e64 v41, |v34|, s28
	v_fma_f32 v51, |v34|, s28, -v41
	v_rndne_f32_e32 v54, v41
	v_fma_f32 v51, |v34|, s29, v51
	v_sub_f32_e32 v41, v41, v54
	v_add_f32_e32 v41, v41, v51
	v_cvt_i32_f32_e32 v54, v54
	v_exp_f32_e32 v41, v41
	v_cmp_ngt_f32_e64 vcc, |v34|, s30
	v_min_f32_e32 v51, 0, v34
	v_ldexp_f32 v41, v41, v54
	v_cndmask_b32_e32 v41, 0, v41, vcc
	v_cmp_nlt_f32_e64 vcc, |v34|, s31
	s_nop 1
	v_cndmask_b32_e32 v34, v50, v41, vcc
	v_add_f32_e32 v41, 1.0, v34
	v_add_f32_e32 v56, -1.0, v41
	v_frexp_mant_f32_e32 v57, v41
	v_cvt_f64_f32_e32 v[54:55], v41
	v_sub_f32_e32 v58, v56, v41
	v_frexp_exp_i32_f64_e32 v54, v[54:55]
	v_cmp_gt_f32_e32 vcc, s35, v57
	v_sub_f32_e32 v56, v34, v56
	v_add_f32_e32 v55, 1.0, v58
	v_subbrev_co_u32_e32 v54, vcc, 0, v54, vcc
	v_add_f32_e32 v55, v56, v55
	v_sub_u32_e32 v56, 0, v54
	v_ldexp_f32 v41, v41, v56
	v_ldexp_f32 v55, v55, v56
	v_add_f32_e32 v56, -1.0, v41
	v_add_f32_e32 v58, 1.0, v41
	v_add_f32_e32 v57, 1.0, v56
	v_add_f32_e32 v59, -1.0, v58
	v_sub_f32_e32 v57, v41, v57
	v_sub_f32_e32 v41, v41, v59
	v_add_f32_e32 v41, v55, v41
	v_add_f32_e32 v59, v55, v57
	v_add_f32_e32 v55, v58, v41
	v_rcp_f32_e32 v62, v55
	v_add_f32_e32 v57, v56, v59
	v_sub_f32_e32 v58, v58, v55
	v_add_f32_e32 v41, v41, v58
	v_mul_f32_e32 v64, v57, v62
	v_mul_f32_e32 v58, v55, v64
	v_fma_f32 v60, v64, v55, -v58
	v_sub_f32_e32 v56, v56, v57
	v_fmac_f32_e32 v60, v64, v41
	v_add_f32_e32 v63, v59, v56
	v_add_f32_e32 v56, v58, v60
	v_sub_f32_e32 v59, v57, v56
	v_mov_b32_e32 v61, v56
	v_pk_add_f32 v[56:57], v[56:57], v[58:59] neg_lo:[0,1] neg_hi:[0,1]
	v_cvt_f32_i32_e32 v54, v54
	v_pk_add_f32 v[56:57], v[56:57], v[60:61] neg_lo:[0,1] neg_hi:[0,1]
	v_cmp_neq_f32_e32 vcc, s34, v34
	v_add_f32_e32 v57, v63, v57
	v_add_f32_e32 v56, v56, v57
	v_add_f32_e32 v57, v59, v56
	v_mul_f32_e32 v61, v62, v57
	v_mul_f32_e32 v58, v55, v61
	v_fma_f32 v60, v61, v55, -v58
	v_sub_f32_e32 v59, v59, v57
	v_fmac_f32_e32 v60, v61, v41
	v_add_f32_e32 v63, v56, v59
	v_add_f32_e32 v65, v64, v61
	v_add_f32_e32 v56, v58, v60
	v_sub_f32_e32 v55, v65, v64
	v_sub_f32_e32 v59, v57, v56
	v_sub_f32_e32 v41, v61, v55
	v_mov_b32_e32 v61, v56
	v_pk_add_f32 v[56:57], v[56:57], v[58:59] neg_lo:[0,1] neg_hi:[0,1]
	s_nop 0
	v_pk_add_f32 v[56:57], v[56:57], v[60:61] neg_lo:[0,1] neg_hi:[0,1]
	s_nop 0
	v_add_f32_e32 v55, v63, v57
	v_add_f32_e32 v55, v56, v55
	v_add_f32_e32 v55, v59, v55
	v_mul_f32_e32 v55, v62, v55
	v_add_f32_e32 v41, v41, v55
	v_add_f32_e32 v55, v65, v41
	v_mul_f32_e32 v56, v55, v55
	v_sub_f32_e32 v58, v55, v65
	v_fmamk_f32 v59, v56, 0x3e9b6dac, v49
	v_ldexp_f32 v57, v55, 1
	v_sub_f32_e32 v58, v41, v58
	v_mul_f32_e32 v55, v55, v56
	v_fmaak_f32 v41, v56, v59, 0x3f2aaada
	v_ldexp_f32 v61, v58, 1
	v_pk_mul_f32 v[58:59], v[54:55], v[40:41]
	s_nop 0
	v_fma_f32 v56, v54, s36, -v58
	v_fmac_f32_e32 v56, 0xb102e308, v54
	v_pk_add_f32 v[54:55], v[58:59], v[56:57]
	v_mov_b32_e32 v60, v58
	v_sub_f32_e32 v41, v55, v57
	v_sub_f32_e32 v41, v59, v41
	v_add_f32_e32 v61, v61, v41
	v_pk_add_f32 v[62:63], v[54:55], v[58:59] neg_lo:[0,1] neg_hi:[0,1]
	v_pk_add_f32 v[58:59], v[54:55], v[60:61]
	v_mov_b32_e32 v57, v54
	v_mov_b32_e32 v63, v59
	v_pk_add_f32 v[66:67], v[56:57], v[62:63] neg_lo:[0,1] neg_hi:[0,1]
	v_pk_add_f32 v[56:57], v[56:57], v[62:63]
	v_mov_b32_e32 v65, v54
	v_pk_add_f32 v[62:63], v[56:57], v[54:55] op_sel:[1,0] op_sel_hi:[0,1] neg_lo:[0,1] neg_hi:[0,1]
	v_mov_b32_e32 v64, v61
	v_mov_b32_e32 v60, v59
	v_mov_b32_e32 v61, v57
	v_pk_mov_b32 v[54:55], v[54:55], v[62:63] op_sel:[1,0]
	v_pk_add_f32 v[58:59], v[58:59], v[62:63] op_sel_hi:[1,0] neg_lo:[0,1] neg_hi:[0,1]
	v_pk_add_f32 v[54:55], v[60:61], v[54:55] neg_lo:[0,1] neg_hi:[0,1]
; DI_ float log_sigmoid(float v) { return fminf(v, 0.f) - log1pf(expf(-fabsf(v))); }
; template <int NS, bool LN, bool WF32, bool WBF, int SKMODE>
; DI_ void row_pass(const float* Xin, float* Xout, bf16_t* XBo, const float* g, const float* b, const float* WsT, float* sk_out, const float* sk_bias, int row0, int nrows, int gw, int NGW, int lane) {
;     ...
;                 const int jo = 8 * grp + (lane >> 3);
;                 if ((lane & 7) == 0) sk_out[(size_t)row * NS + jo] = (SKMODE == 1) ? log_sigmoid(a[0] + sk_bias[jo]) : a[0];
	v_mov_b32_e32 v58, v66
	v_pk_add_f32 v[54:55], v[64:65], v[54:55] neg_lo:[0,1] neg_hi:[0,1]
	v_mov_b32_e32 v67, v57
	v_pk_add_f32 v[58:59], v[58:59], v[54:55]
	s_nop 0
	v_pk_add_f32 v[60:61], v[58:59], v[58:59] op_sel:[0,1] op_sel_hi:[1,0]
	s_nop 0
	v_pk_add_f32 v[56:57], v[56:57], v[60:61] op_sel:[1,0] op_sel_hi:[0,1]
	v_mov_b32_e32 v59, v56
	v_mov_b32_e32 v55, v60
	v_pk_add_f32 v[60:61], v[58:59], v[66:67] neg_lo:[0,1] neg_hi:[0,1]
	s_nop 0
	v_sub_f32_e32 v41, v58, v60
	v_pk_add_f32 v[54:55], v[54:55], v[60:61] neg_lo:[0,1] neg_hi:[0,1]
	v_sub_f32_e32 v41, v66, v41
	v_add_f32_e32 v41, v54, v41
	v_add_f32_e32 v41, v41, v55
	v_add_f32_e32 v41, v56, v41
	v_cndmask_b32_e32 v41, v50, v41, vcc
	v_cmp_lt_f32_e64 vcc, |v34|, s37
	s_nop 1
	v_cndmask_b32_e32 v34, v41, v34, vcc
	v_sub_f32_e32 v34, v51, v34
	global_store_dword v[22:23], v34, off
	v_add_f32_e32 v34, v13, v24
	v_mul_f32_e64 v41, |v34|, s28
	v_fma_f32 v51, |v34|, s28, -v41
	v_rndne_f32_e32 v54, v41
	v_fma_f32 v51, |v34|, s29, v51
	v_sub_f32_e32 v41, v41, v54
	v_add_f32_e32 v41, v41, v51
	v_cvt_i32_f32_e32 v54, v54
	v_exp_f32_e32 v41, v41
	v_cmp_ngt_f32_e64 vcc, |v34|, s30
	v_min_f32_e32 v51, 0, v34
	v_ldexp_f32 v41, v41, v54
	v_cndmask_b32_e32 v41, 0, v41, vcc
	v_cmp_nlt_f32_e64 vcc, |v34|, s31
	s_nop 1
	v_cndmask_b32_e32 v34, v50, v41, vcc
	v_add_f32_e32 v41, 1.0, v34
	v_add_f32_e32 v56, -1.0, v41
	v_frexp_mant_f32_e32 v57, v41
	v_cvt_f64_f32_e32 v[54:55], v41
	v_sub_f32_e32 v58, v56, v41
	v_frexp_exp_i32_f64_e32 v54, v[54:55]
	v_cmp_gt_f32_e32 vcc, s35, v57
	v_sub_f32_e32 v56, v34, v56
	v_add_f32_e32 v55, 1.0, v58
	v_subbrev_co_u32_e32 v54, vcc, 0, v54, vcc
	v_add_f32_e32 v55, v56, v55
	v_sub_u32_e32 v56, 0, v54
	v_ldexp_f32 v41, v41, v56
	v_ldexp_f32 v55, v55, v56
	v_add_f32_e32 v56, -1.0, v41
	v_add_f32_e32 v58, 1.0, v41
	v_add_f32_e32 v57, 1.0, v56
	v_add_f32_e32 v59, -1.0, v58
	v_sub_f32_e32 v57, v41, v57
	v_sub_f32_e32 v41, v41, v59
	v_add_f32_e32 v41, v55, v41
	v_add_f32_e32 v59, v55, v57
	v_add_f32_e32 v55, v58, v41
	v_rcp_f32_e32 v62, v55
	v_add_f32_e32 v57, v56, v59
	v_sub_f32_e32 v58, v58, v55
	v_add_f32_e32 v41, v41, v58
	v_mul_f32_e32 v64, v57, v62
	v_mul_f32_e32 v58, v55, v64
	v_fma_f32 v60, v64, v55, -v58
	v_sub_f32_e32 v56, v56, v57
	v_fmac_f32_e32 v60, v64, v41
	v_add_f32_e32 v63, v59, v56
	v_add_f32_e32 v56, v58, v60
	v_sub_f32_e32 v59, v57, v56
	v_mov_b32_e32 v61, v56
	v_pk_add_f32 v[56:57], v[56:57], v[58:59] neg_lo:[0,1] neg_hi:[0,1]
	v_cvt_f32_i32_e32 v54, v54
	v_pk_add_f32 v[56:57], v[56:57], v[60:61] neg_lo:[0,1] neg_hi:[0,1]
	v_cmp_neq_f32_e32 vcc, s34, v34
	v_add_f32_e32 v57, v63, v57
	v_add_f32_e32 v56, v56, v57
	v_add_f32_e32 v57, v59, v56
	v_mul_f32_e32 v61, v62, v57
	v_mul_f32_e32 v58, v55, v61
	v_fma_f32 v60, v61, v55, -v58
	v_sub_f32_e32 v59, v59, v57
	v_fmac_f32_e32 v60, v61, v41
	v_add_f32_e32 v63, v56, v59
	v_add_f32_e32 v65, v64, v61
	v_add_f32_e32 v56, v58, v60
	v_sub_f32_e32 v55, v65, v64
	v_sub_f32_e32 v59, v57, v56
	v_sub_f32_e32 v41, v61, v55
	v_mov_b32_e32 v61, v56
	v_pk_add_f32 v[56:57], v[56:57], v[58:59] neg_lo:[0,1] neg_hi:[0,1]
	s_nop 0
	v_pk_add_f32 v[56:57], v[56:57], v[60:61] neg_lo:[0,1] neg_hi:[0,1]
	s_nop 0
	v_add_f32_e32 v55, v63, v57
	v_add_f32_e32 v55, v56, v55
	v_add_f32_e32 v55, v59, v55
	v_mul_f32_e32 v55, v62, v55
	v_add_f32_e32 v41, v41, v55
	v_add_f32_e32 v55, v65, v41
	v_mul_f32_e32 v56, v55, v55
	v_sub_f32_e32 v58, v55, v65
	v_fmamk_f32 v59, v56, 0x3e9b6dac, v49
	v_ldexp_f32 v57, v55, 1
	v_sub_f32_e32 v58, v41, v58
	v_mul_f32_e32 v55, v55, v56
	v_fmaak_f32 v41, v56, v59, 0x3f2aaada
	v_ldexp_f32 v61, v58, 1
	v_pk_mul_f32 v[58:59], v[54:55], v[40:41]
	s_nop 0
	v_fma_f32 v56, v54, s36, -v58
	v_fmac_f32_e32 v56, 0xb102e308, v54
	v_pk_add_f32 v[54:55], v[58:59], v[56:57]
	v_mov_b32_e32 v60, v58
	v_sub_f32_e32 v41, v55, v57
	v_sub_f32_e32 v41, v59, v41
	v_add_f32_e32 v61, v61, v41
	v_pk_add_f32 v[62:63], v[54:55], v[58:59] neg_lo:[0,1] neg_hi:[0,1]
	v_pk_add_f32 v[58:59], v[54:55], v[60:61]
	v_mov_b32_e32 v57, v54
	v_mov_b32_e32 v63, v59
	v_pk_add_f32 v[66:67], v[56:57], v[62:63] neg_lo:[0,1] neg_hi:[0,1]
	v_pk_add_f32 v[56:57], v[56:57], v[62:63]
	v_mov_b32_e32 v65, v54
	v_pk_add_f32 v[62:63], v[56:57], v[54:55] op_sel:[1,0] op_sel_hi:[0,1] neg_lo:[0,1] neg_hi:[0,1]
	v_mov_b32_e32 v64, v61
	v_mov_b32_e32 v60, v59
	v_mov_b32_e32 v61, v57
	v_pk_mov_b32 v[54:55], v[54:55], v[62:63] op_sel:[1,0]
	v_pk_add_f32 v[58:59], v[58:59], v[62:63] op_sel_hi:[1,0] neg_lo:[0,1] neg_hi:[0,1]
	v_pk_add_f32 v[54:55], v[60:61], v[54:55] neg_lo:[0,1] neg_hi:[0,1]
	v_mov_b32_e32 v58, v66
	v_pk_add_f32 v[54:55], v[64:65], v[54:55] neg_lo:[0,1] neg_hi:[0,1]
	v_mov_b32_e32 v67, v57
	v_pk_add_f32 v[58:59], v[58:59], v[54:55]
	s_nop 0
	v_pk_add_f32 v[60:61], v[58:59], v[58:59] op_sel:[0,1] op_sel_hi:[1,0]
	s_nop 0
	v_pk_add_f32 v[56:57], v[56:57], v[60:61] op_sel:[1,0] op_sel_hi:[0,1]
	v_mov_b32_e32 v59, v56
	v_mov_b32_e32 v55, v60
	v_pk_add_f32 v[60:61], v[58:59], v[66:67] neg_lo:[0,1] neg_hi:[0,1]
	s_nop 0
	v_sub_f32_e32 v41, v58, v60
	v_pk_add_f32 v[54:55], v[54:55], v[60:61] neg_lo:[0,1] neg_hi:[0,1]
	v_sub_f32_e32 v41, v66, v41
	v_add_f32_e32 v41, v54, v41
	v_add_f32_e32 v41, v41, v55
	v_add_f32_e32 v41, v56, v41
	v_cndmask_b32_e32 v41, v50, v41, vcc
	v_cmp_lt_f32_e64 vcc, |v34|, s37
	s_nop 1
	v_cndmask_b32_e32 v34, v41, v34, vcc
	v_sub_f32_e32 v34, v51, v34
	global_store_dword v[22:23], v34, off offset:64
	v_add_f32_e32 v34, v14, v24
	v_mul_f32_e64 v41, |v34|, s28
	v_fma_f32 v51, |v34|, s28, -v41
	v_rndne_f32_e32 v54, v41
	v_fma_f32 v51, |v34|, s29, v51
	v_sub_f32_e32 v41, v41, v54
	v_add_f32_e32 v41, v41, v51
	v_cvt_i32_f32_e32 v54, v54
; DI_ float log_sigmoid(float v) { return fminf(v, 0.f) - log1pf(expf(-fabsf(v))); }
; template <int NS, bool LN, bool WF32, bool WBF, int SKMODE>
; DI_ void row_pass(const float* Xin, float* Xout, bf16_t* XBo, const float* g, const float* b, const float* WsT, float* sk_out, const float* sk_bias, int row0, int nrows, int gw, int NGW, int lane) {
;     ...
;                 const int jo = 8 * grp + (lane >> 3);
;                 if ((lane & 7) == 0) sk_out[(size_t)row * NS + jo] = (SKMODE == 1) ? log_sigmoid(a[0] + sk_bias[jo]) : a[0];
	v_exp_f32_e32 v41, v41
	v_cmp_ngt_f32_e64 vcc, |v34|, s30
	v_min_f32_e32 v51, 0, v34
	v_ldexp_f32 v41, v41, v54
	v_cndmask_b32_e32 v41, 0, v41, vcc
	v_cmp_nlt_f32_e64 vcc, |v34|, s31
	s_nop 1
	v_cndmask_b32_e32 v34, v50, v41, vcc
	v_add_f32_e32 v41, 1.0, v34
	v_add_f32_e32 v56, -1.0, v41
	v_frexp_mant_f32_e32 v57, v41
	v_cvt_f64_f32_e32 v[54:55], v41
	v_sub_f32_e32 v58, v56, v41
	v_frexp_exp_i32_f64_e32 v54, v[54:55]
	v_cmp_gt_f32_e32 vcc, s35, v57
	v_sub_f32_e32 v56, v34, v56
	v_add_f32_e32 v55, 1.0, v58
	v_subbrev_co_u32_e32 v54, vcc, 0, v54, vcc
	v_add_f32_e32 v55, v56, v55
	v_sub_u32_e32 v56, 0, v54
	v_ldexp_f32 v41, v41, v56
	v_ldexp_f32 v55, v55, v56
	v_add_f32_e32 v56, -1.0, v41
	v_add_f32_e32 v58, 1.0, v41
	v_add_f32_e32 v57, 1.0, v56
	v_add_f32_e32 v59, -1.0, v58
	v_sub_f32_e32 v57, v41, v57
	v_sub_f32_e32 v41, v41, v59
	v_add_f32_e32 v41, v55, v41
	v_add_f32_e32 v59, v55, v57
	v_add_f32_e32 v55, v58, v41
	v_rcp_f32_e32 v62, v55
	v_add_f32_e32 v57, v56, v59
	v_sub_f32_e32 v58, v58, v55
	v_add_f32_e32 v41, v41, v58
	v_mul_f32_e32 v64, v57, v62
	v_mul_f32_e32 v58, v55, v64
	v_fma_f32 v60, v64, v55, -v58
	v_sub_f32_e32 v56, v56, v57
	v_fmac_f32_e32 v60, v64, v41
	v_add_f32_e32 v63, v59, v56
	v_add_f32_e32 v56, v58, v60
	v_sub_f32_e32 v59, v57, v56
	v_mov_b32_e32 v61, v56
	v_pk_add_f32 v[56:57], v[56:57], v[58:59] neg_lo:[0,1] neg_hi:[0,1]
	v_cvt_f32_i32_e32 v54, v54
	v_pk_add_f32 v[56:57], v[56:57], v[60:61] neg_lo:[0,1] neg_hi:[0,1]
	v_cmp_neq_f32_e32 vcc, s34, v34
	v_add_f32_e32 v57, v63, v57
	v_add_f32_e32 v56, v56, v57
	v_add_f32_e32 v57, v59, v56
	v_mul_f32_e32 v61, v62, v57
	v_mul_f32_e32 v58, v55, v61
	v_fma_f32 v60, v61, v55, -v58
	v_sub_f32_e32 v59, v59, v57
	v_fmac_f32_e32 v60, v61, v41
	v_add_f32_e32 v63, v56, v59
	v_add_f32_e32 v65, v64, v61
	v_add_f32_e32 v56, v58, v60
	v_sub_f32_e32 v55, v65, v64
	v_sub_f32_e32 v59, v57, v56
	v_sub_f32_e32 v41, v61, v55
	v_mov_b32_e32 v61, v56
	v_pk_add_f32 v[56:57], v[56:57], v[58:59] neg_lo:[0,1] neg_hi:[0,1]
	s_nop 0
	v_pk_add_f32 v[56:57], v[56:57], v[60:61] neg_lo:[0,1] neg_hi:[0,1]
	s_nop 0
	v_add_f32_e32 v55, v63, v57
	v_add_f32_e32 v55, v56, v55
	v_add_f32_e32 v55, v59, v55
	v_mul_f32_e32 v55, v62, v55
	v_add_f32_e32 v41, v41, v55
	v_add_f32_e32 v55, v65, v41
	v_mul_f32_e32 v56, v55, v55
	v_sub_f32_e32 v58, v55, v65
	v_fmamk_f32 v59, v56, 0x3e9b6dac, v49
	v_ldexp_f32 v57, v55, 1
	v_sub_f32_e32 v58, v41, v58
	v_mul_f32_e32 v55, v55, v56
	v_fmaak_f32 v41, v56, v59, 0x3f2aaada
	v_ldexp_f32 v61, v58, 1
	v_pk_mul_f32 v[58:59], v[54:55], v[40:41]
	s_nop 0
	v_fma_f32 v56, v54, s36, -v58
	v_fmac_f32_e32 v56, 0xb102e308, v54
	v_pk_add_f32 v[54:55], v[58:59], v[56:57]
	v_mov_b32_e32 v60, v58
	v_sub_f32_e32 v41, v55, v57
	v_sub_f32_e32 v41, v59, v41
	v_add_f32_e32 v61, v61, v41
	v_pk_add_f32 v[62:63], v[54:55], v[58:59] neg_lo:[0,1] neg_hi:[0,1]
	v_pk_add_f32 v[58:59], v[54:55], v[60:61]
	v_mov_b32_e32 v57, v54
	v_mov_b32_e32 v63, v59
	v_pk_add_f32 v[66:67], v[56:57], v[62:63] neg_lo:[0,1] neg_hi:[0,1]
	v_pk_add_f32 v[56:57], v[56:57], v[62:63]
	v_mov_b32_e32 v65, v54
	v_pk_add_f32 v[62:63], v[56:57], v[54:55] op_sel:[1,0] op_sel_hi:[0,1] neg_lo:[0,1] neg_hi:[0,1]
	v_mov_b32_e32 v64, v61
	v_mov_b32_e32 v60, v59
	v_mov_b32_e32 v61, v57
	v_pk_mov_b32 v[54:55], v[54:55], v[62:63] op_sel:[1,0]
	v_pk_add_f32 v[58:59], v[58:59], v[62:63] op_sel_hi:[1,0] neg_lo:[0,1] neg_hi:[0,1]
	v_pk_add_f32 v[54:55], v[60:61], v[54:55] neg_lo:[0,1] neg_hi:[0,1]
	v_mov_b32_e32 v58, v66
	v_pk_add_f32 v[54:55], v[64:65], v[54:55] neg_lo:[0,1] neg_hi:[0,1]
	v_mov_b32_e32 v67, v57
	v_pk_add_f32 v[58:59], v[58:59], v[54:55]
	s_nop 0
	v_pk_add_f32 v[60:61], v[58:59], v[58:59] op_sel:[0,1] op_sel_hi:[1,0]
	s_nop 0
	v_pk_add_f32 v[56:57], v[56:57], v[60:61] op_sel:[1,0] op_sel_hi:[0,1]
	v_mov_b32_e32 v59, v56
	v_mov_b32_e32 v55, v60
	v_pk_add_f32 v[60:61], v[58:59], v[66:67] neg_lo:[0,1] neg_hi:[0,1]
	s_nop 0
	v_sub_f32_e32 v41, v58, v60
	v_pk_add_f32 v[54:55], v[54:55], v[60:61] neg_lo:[0,1] neg_hi:[0,1]
	v_sub_f32_e32 v41, v66, v41
	v_add_f32_e32 v41, v54, v41
	v_add_f32_e32 v41, v41, v55
	v_add_f32_e32 v41, v56, v41
	v_cndmask_b32_e32 v41, v50, v41, vcc
	v_cmp_lt_f32_e64 vcc, |v34|, s37
	s_nop 1
	v_cndmask_b32_e32 v34, v41, v34, vcc
	v_sub_f32_e32 v34, v51, v34
	global_store_dword v[22:23], v34, off offset:128
	v_add_f32_e32 v34, v15, v24
	v_mul_f32_e64 v41, |v34|, s28
	v_fma_f32 v51, |v34|, s28, -v41
	v_rndne_f32_e32 v54, v41
	v_fma_f32 v51, |v34|, s29, v51
	v_sub_f32_e32 v41, v41, v54
	v_add_f32_e32 v41, v41, v51
	v_cvt_i32_f32_e32 v54, v54
	v_exp_f32_e32 v41, v41
	v_cmp_ngt_f32_e64 vcc, |v34|, s30
	v_min_f32_e32 v51, 0, v34
	v_ldexp_f32 v41, v41, v54
	v_cndmask_b32_e32 v41, 0, v41, vcc
	v_cmp_nlt_f32_e64 vcc, |v34|, s31
	s_nop 1
	v_cndmask_b32_e32 v34, v50, v41, vcc
	v_add_f32_e32 v41, 1.0, v34
	v_add_f32_e32 v56, -1.0, v41
	v_frexp_mant_f32_e32 v57, v41
	v_cvt_f64_f32_e32 v[54:55], v41
	v_sub_f32_e32 v58, v56, v41
	v_frexp_exp_i32_f64_e32 v54, v[54:55]
	v_cmp_gt_f32_e32 vcc, s35, v57
	v_sub_f32_e32 v56, v34, v56
	v_add_f32_e32 v55, 1.0, v58
	v_subbrev_co_u32_e32 v54, vcc, 0, v54, vcc
	v_add_f32_e32 v55, v56, v55
	v_sub_u32_e32 v56, 0, v54
	v_ldexp_f32 v41, v41, v56
	v_ldexp_f32 v55, v55, v56
	v_add_f32_e32 v56, -1.0, v41
	v_add_f32_e32 v58, 1.0, v41
	v_add_f32_e32 v57, 1.0, v56
	v_add_f32_e32 v59, -1.0, v58
	v_sub_f32_e32 v57, v41, v57
	v_sub_f32_e32 v41, v41, v59
	v_add_f32_e32 v41, v55, v41
	v_add_f32_e32 v59, v55, v57
; DI_ float log_sigmoid(float v) { return fminf(v, 0.f) - log1pf(expf(-fabsf(v))); }
; template <int NS, bool LN, bool WF32, bool WBF, int SKMODE>
; DI_ void row_pass(const float* Xin, float* Xout, bf16_t* XBo, const float* g, const float* b, const float* WsT, float* sk_out, const float* sk_bias, int row0, int nrows, int gw, int NGW, int lane) {
;     f32x4 nv[4];
;     if (row0 + gw < row0 + nrows) { const f32x4* xr = (const f32x4*)(Xin + (size_t)(row0 + gw) * D) + lane;
; #pragma unroll
;         for (int j = 0; j < 4; ++j) nv[j] = xr[64 * j]; }
;     for (int row = row0 + gw; row < row0 + nrows; row += NGW) {
;         f32x4 v[4];
; #pragma unroll
;         for (int j = 0; j < 4; ++j) v[j] = nv[j];
;         if (row + NGW < row0 + nrows) { const f32x4* xr = (const f32x4*)(Xin + (size_t)(row + NGW) * D) + lane;
; #pragma unroll
;             for (int j = 0; j < 4; ++j) nv[j] = xr[64 * j]; }
;         if (LN) {
;             float s = 0.f;
; #pragma unroll
;             for (int j = 0; j < 4; ++j) s += (v[j][0] + v[j][1]) + (v[j][2] + v[j][3]);
;             const float mean = wave_sum(s) * (1.f / D); float s2 = 0.f;
; #pragma unroll
;             for (int j = 0; j < 4; ++j) { v[j] = v[j] - mean; s2 += (v[j][0] * v[j][0] + v[j][1] * v[j][1]) + (v[j][2] * v[j][2] + v[j][3] * v[j][3]); }
;             const float rstd = 1.f / sqrtf(wave_sum(s2) * (1.f / D) + LN_EPS);
; #pragma unroll
;             for (int j = 0; j < 4; ++j) { const f32x4 gg = ((const f32x4*)g)[lane + 64 * j], bb = ((const f32x4*)b)[lane + 64 * j]; v[j] = v[j] * rstd * gg + bb; }
;         }
;         if (WF32) {
;             f32x4* xo = (f32x4*)(Xout + (size_t)row * D) + lane;
; #pragma unroll
;             for (int j = 0; j < 4; ++j) xo[64 * j] = v[j];
;         }
;         if (WBF) {
;             u32x2* xo = (u32x2*)(XBo + (size_t)row * D) + lane;
; #pragma unroll
;             for (int j = 0; j < 4; ++j) { u32x2 w; w.x = pk2(v[j][0], v[j][1]); w.y = pk2(v[j][2], v[j][3]); xo[64 * j] = w; }
;         }
;         if (NS > 0) {
; #pragma unroll 1
;             for (int grp = 0; grp < NS / 8; ++grp) {
;                 float a[8];
; #pragma unroll
;                 for (int jc = 0; jc < 8; ++jc) {
;                     float s = 0.f;
; #pragma unroll
	v_add_f32_e32 v55, v58, v41
	v_rcp_f32_e32 v62, v55
	v_add_f32_e32 v57, v56, v59
	v_sub_f32_e32 v58, v58, v55
	v_add_f32_e32 v41, v41, v58
	v_mul_f32_e32 v64, v57, v62
	v_mul_f32_e32 v58, v55, v64
	v_fma_f32 v60, v64, v55, -v58
	v_sub_f32_e32 v56, v56, v57
	v_fmac_f32_e32 v60, v64, v41
	v_add_f32_e32 v63, v59, v56
	v_add_f32_e32 v56, v58, v60
	v_sub_f32_e32 v59, v57, v56
	v_mov_b32_e32 v61, v56
	v_pk_add_f32 v[56:57], v[56:57], v[58:59] neg_lo:[0,1] neg_hi:[0,1]
	v_cvt_f32_i32_e32 v54, v54
	v_pk_add_f32 v[56:57], v[56:57], v[60:61] neg_lo:[0,1] neg_hi:[0,1]
	v_cmp_neq_f32_e32 vcc, s34, v34
	v_add_f32_e32 v57, v63, v57
	v_add_f32_e32 v56, v56, v57
	v_add_f32_e32 v57, v59, v56
	v_mul_f32_e32 v61, v62, v57
	v_mul_f32_e32 v58, v55, v61
	v_fma_f32 v60, v61, v55, -v58
	v_sub_f32_e32 v59, v59, v57
	v_fmac_f32_e32 v60, v61, v41
	v_add_f32_e32 v63, v56, v59
	v_add_f32_e32 v65, v64, v61
	v_add_f32_e32 v56, v58, v60
	v_sub_f32_e32 v55, v65, v64
	v_sub_f32_e32 v59, v57, v56
	v_sub_f32_e32 v41, v61, v55
	v_mov_b32_e32 v61, v56
	v_pk_add_f32 v[56:57], v[56:57], v[58:59] neg_lo:[0,1] neg_hi:[0,1]
	s_nop 0
	v_pk_add_f32 v[56:57], v[56:57], v[60:61] neg_lo:[0,1] neg_hi:[0,1]
	s_nop 0
	v_add_f32_e32 v55, v63, v57
	v_add_f32_e32 v55, v56, v55
	v_add_f32_e32 v55, v59, v55
	v_mul_f32_e32 v55, v62, v55
	v_add_f32_e32 v41, v41, v55
	v_add_f32_e32 v55, v65, v41
	v_mul_f32_e32 v56, v55, v55
	v_sub_f32_e32 v58, v55, v65
	v_fmamk_f32 v59, v56, 0x3e9b6dac, v49
	v_ldexp_f32 v57, v55, 1
	v_sub_f32_e32 v58, v41, v58
	v_mul_f32_e32 v55, v55, v56
	v_fmaak_f32 v41, v56, v59, 0x3f2aaada
	v_ldexp_f32 v61, v58, 1
	v_pk_mul_f32 v[58:59], v[54:55], v[40:41]
	s_nop 0
	v_fma_f32 v56, v54, s36, -v58
	v_fmac_f32_e32 v56, 0xb102e308, v54
	v_pk_add_f32 v[54:55], v[58:59], v[56:57]
	v_mov_b32_e32 v60, v58
	v_sub_f32_e32 v41, v55, v57
	v_sub_f32_e32 v41, v59, v41
	v_add_f32_e32 v61, v61, v41
	v_pk_add_f32 v[62:63], v[54:55], v[58:59] neg_lo:[0,1] neg_hi:[0,1]
	v_pk_add_f32 v[58:59], v[54:55], v[60:61]
	v_mov_b32_e32 v57, v54
	v_mov_b32_e32 v63, v59
	v_pk_add_f32 v[66:67], v[56:57], v[62:63] neg_lo:[0,1] neg_hi:[0,1]
	v_pk_add_f32 v[56:57], v[56:57], v[62:63]
	v_mov_b32_e32 v65, v54
	v_pk_add_f32 v[62:63], v[56:57], v[54:55] op_sel:[1,0] op_sel_hi:[0,1] neg_lo:[0,1] neg_hi:[0,1]
	v_mov_b32_e32 v64, v61
	v_mov_b32_e32 v60, v59
	v_mov_b32_e32 v61, v57
	v_pk_mov_b32 v[54:55], v[54:55], v[62:63] op_sel:[1,0]
	v_pk_add_f32 v[58:59], v[58:59], v[62:63] op_sel_hi:[1,0] neg_lo:[0,1] neg_hi:[0,1]
	v_pk_add_f32 v[54:55], v[60:61], v[54:55] neg_lo:[0,1] neg_hi:[0,1]
	v_mov_b32_e32 v58, v66
	v_pk_add_f32 v[54:55], v[64:65], v[54:55] neg_lo:[0,1] neg_hi:[0,1]
	v_mov_b32_e32 v67, v57
	v_pk_add_f32 v[58:59], v[58:59], v[54:55]
	s_nop 0
	v_pk_add_f32 v[60:61], v[58:59], v[58:59] op_sel:[0,1] op_sel_hi:[1,0]
	s_nop 0
	v_pk_add_f32 v[56:57], v[56:57], v[60:61] op_sel:[1,0] op_sel_hi:[0,1]
	v_mov_b32_e32 v59, v56
	v_mov_b32_e32 v55, v60
	v_pk_add_f32 v[60:61], v[58:59], v[66:67] neg_lo:[0,1] neg_hi:[0,1]
	s_nop 0
	v_sub_f32_e32 v41, v58, v60
	v_pk_add_f32 v[54:55], v[54:55], v[60:61] neg_lo:[0,1] neg_hi:[0,1]
	v_sub_f32_e32 v41, v66, v41
	v_add_f32_e32 v41, v54, v41
	v_add_f32_e32 v41, v41, v55
	v_add_f32_e32 v41, v56, v41
	v_cndmask_b32_e32 v41, v50, v41, vcc
	v_cmp_lt_f32_e64 vcc, |v34|, s37
	s_nop 1
	v_cndmask_b32_e32 v34, v41, v34, vcc
	v_sub_f32_e32 v34, v51, v34
	global_store_dword v[22:23], v34, off offset:192
	s_branch .LBB0_50
.Lmy_p0_orig:
	s_ashr_i32 s21, s20, 31
	s_lshl_b64 s[0:1], s[20:21], 12
	v_and_b32_e32 v19, 63, v18
	s_add_u32 s0, s56, s0
	s_addc_u32 s1, s57, s1
	v_lshlrev_b32_e32 v34, 4, v19
	global_load_dwordx4 v[2:5], v34, s[0:1]
	global_load_dwordx4 v[6:9], v34, s[0:1] offset:1024
	global_load_dwordx4 v[10:13], v34, s[0:1] offset:2048
	global_load_dwordx4 v[14:17], v34, s[0:1] offset:3072
	v_mov_b32_e32 v35, 0
	v_lshlrev_b32_e32 v20, 3, v19
	v_mov_b32_e32 v21, v35
	v_cmp_gt_u32_e64 s[0:1], 32, v19
	v_mbcnt_hi_u32_b32 v19, -1, v149
	v_lshl_add_u64 v[38:39], s[86:87], 0, v[20:21]
	v_and_b32_e32 v21, 64, v19
	v_xor_b32_e32 v20, 32, v19
	v_add_u32_e32 v21, 64, v21
	v_cmp_lt_i32_e32 vcc, v20, v21
	v_lshl_add_u64 v[36:37], s[56:57], 0, v[34:35]
	v_add_u32_e32 v1, 0, v34
	v_cndmask_b32_e32 v20, v19, v20, vcc
	v_lshlrev_b32_e32 v42, 2, v20
	v_and_b32_e32 v20, 16, v18
	v_cmp_eq_u32_e64 s[10:11], 0, v20
	v_xor_b32_e32 v20, 16, v19
	v_cmp_lt_i32_e32 vcc, v20, v21
	v_bfe_u32 v48, v18, 3, 3
	s_mov_b32 s28, 0xbfb8aa3b
	v_cndmask_b32_e32 v20, v19, v20, vcc
	v_lshlrev_b32_e32 v43, 2, v20
	v_and_b32_e32 v20, 8, v18
	v_cmp_eq_u32_e64 s[6:7], 0, v20
	v_xor_b32_e32 v20, 8, v19
	v_cmp_lt_i32_e32 vcc, v20, v21
	s_mov_b32 s29, 0xb2a5705f
	s_mov_b32 s30, 0x42ce8ed0
	v_cndmask_b32_e32 v20, v19, v20, vcc
	v_lshlrev_b32_e32 v44, 2, v20
	v_xor_b32_e32 v20, 4, v19
	v_cmp_lt_i32_e32 vcc, v20, v21
	s_mov_b32 s31, 0xc2b17218
	s_mov_b32 s34, 0x7f800000
	v_cndmask_b32_e32 v20, v19, v20, vcc
	v_lshlrev_b32_e32 v45, 2, v20
	v_xor_b32_e32 v20, 2, v19
	v_cmp_lt_i32_e32 vcc, v20, v21
	s_mov_b32 s35, 0x3f2aaaab
	v_mov_b32_e32 v49, 0x3ecc95a3
	v_cndmask_b32_e32 v20, v19, v20, vcc
	v_lshlrev_b32_e32 v46, 2, v20
	v_xor_b32_e32 v20, 1, v19
	v_cmp_lt_i32_e32 vcc, v20, v21
	s_mov_b32 s36, 0x3f317218
	s_mov_b32 s37, 0x33800000
	v_cndmask_b32_e32 v19, v19, v20, vcc
	v_lshlrev_b32_e32 v47, 2, v19
	v_and_b32_e32 v19, 7, v18
	v_cmp_eq_u32_e64 s[8:9], 0, v19
	v_mov_b32_e32 v50, 0x7f800000
	v_mov_b32_e32 v40, 0x3f317218
	s_branch .LBB0_43

; DI_ float bf_lo(unsigned w) { return __uint_as_float(w << 16); }
; DI_ float bf_hi(unsigned w) { return __uint_as_float(w & 0xffff0000u); }
; template <int NS>
; DI_ void skinny_pass_bf16(const bf16_t* XBrows, int nrows, const float* WsT, float* sk_out, int gw, int NGW, int lane) {
;     for (int row = gw; row < nrows; row += 4 * NGW) {
;         float v[4][16];
; #pragma unroll
;         for (int r = 0; r < 4; ++r) { const int rr = row + r * NGW < nrows ? row + r * NGW : row; const u32x2* rp = (const u32x2*)(XBrows + (size_t)rr * D) + lane;
; #pragma unroll
;             for (int j = 0; j < 4; ++j) { const u32x2 w = rp[64 * j]; v[r][4 * j] = bf_lo(w.x); v[r][4 * j + 1] = bf_hi(w.x); v[r][4 * j + 2] = bf_lo(w.y); v[r][4 * j + 3] = bf_hi(w.y); } }
; #pragma unroll 1
;         for (int grp = 0; grp < NS / 8; ++grp) {
;             float a[4][8];
; #pragma unroll
;             for (int jc = 0; jc < 8; ++jc) {
;                 const float* wp = WsT + (8 * grp + jc) * WST + 4 * lane; float s0 = 0.f, s1 = 0.f, s2 = 0.f, s3 = 0.f;
; #pragma unroll
;                 for (int j = 0; j < 4; ++j) { const f32x4 w = *(const f32x4*)(wp + 256 * j);
;                     s0 += (v[0][4 * j] * w[0] + v[0][4 * j + 1] * w[1]) + (v[0][4 * j + 2] * w[2] + v[0][4 * j + 3] * w[3]);
;                     s1 += (v[1][4 * j] * w[0] + v[1][4 * j + 1] * w[1]) + (v[1][4 * j + 2] * w[2] + v[1][4 * j + 3] * w[3]);
;                     s2 += (v[2][4 * j] * w[0] + v[2][4 * j + 1] * w[1]) + (v[2][4 * j + 2] * w[2] + v[2][4 * j + 3] * w[3]);
;                     s3 += (v[3][4 * j] * w[0] + v[3][4 * j + 1] * w[1]) + (v[3][4 * j + 2] * w[2] + v[3][4 * j + 3] * w[3]); }
;                 a[0][jc] = s0; a[1][jc] = s1; a[2][jc] = s2; a[3][jc] = s3;
.LBB0_468:
	s_or_b64 exec, exec, s[6:7]
	v_mov_b32_e32 v0, v187
	s_xor_b64 s[62:63], s[0:1], -1
	s_waitcnt lgkmcnt(0)
	s_barrier
	s_nop 0
	v_readfirstlane_b32 s0, v0
	s_ashr_i32 s4, s0, 6
	s_add_i32 s64, s4, s60
	s_cmpk_gt_i32 s64, 0x3fff
	s_cbranch_scc1 .LBB0_482
	s_cmpk_lg_i32 s94, 0x800
	s_cbranch_scc1 .Lmy_sk_orig
	s_lshr_b32 s5, s4, 1
	s_and_b32 s6, s4, 1
	s_lshl_b32 s7, s2, 6
	s_lshl_b32 s5, s5, 4
	s_add_i32 s7, s7, s5
	s_lshl_b32 s6, s6, 4
	v_and_b32_e32 v1, 63, v0
	v_and_b32_e32 v2, 15, v1
	v_lshrrev_b32_e32 v3, 4, v1
	v_add_u32_e32 v4, s7, v2
	v_lshlrev_b32_e32 v4, 11, v4
	v_lshl_add_u32 v4, v3, 9, v4
	v_mov_b32_e32 v5, 0
	v_lshl_add_u64 v[6:7], s[54:55], 0, v[4:5]
	v_add_u32_e32 v8, s6, v2
	v_mul_u32_u24_e32 v9, 0x1010, v8
	v_lshl_add_u32 v9, v3, 10, v9
	v_lshl_add_u32 v10, v3, 2, s7
	v_lshlrev_b32_e32 v10, 7, v10
	v_lshl_add_u32 v10, v8, 2, v10
	v_mov_b32_e32 v11, 0
	v_lshl_add_u64 v[10:11], s[28:29], 0, v[10:11]
	v_mov_b32_e32 v12, 0
	v_mov_b32_e32 v13, 0
	v_mov_b32_e32 v14, 0
	v_mov_b32_e32 v15, 0
	v_mov_b32_e32 v16, 0
	v_mov_b32_e32 v17, 0
	v_mov_b32_e32 v18, 0
	v_mov_b32_e32 v19, 0
	global_load_dwordx4 v[20:23], v[6:7], off
	global_load_dwordx4 v[24:27], v[6:7], off offset:16
	global_load_dwordx4 v[28:31], v[6:7], off offset:32
	global_load_dwordx4 v[32:35], v[6:7], off offset:48
	global_load_dwordx4 v[50:53], v[6:7], off offset:64
	global_load_dwordx4 v[54:57], v[6:7], off offset:80
	global_load_dwordx4 v[58:61], v[6:7], off offset:96
	global_load_dwordx4 v[62:65], v[6:7], off offset:112
	ds_read_b128 v[66:69], v9
	ds_read_b128 v[70:73], v9 offset:16
	ds_read_b128 v[74:77], v9 offset:32
	ds_read_b128 v[78:81], v9 offset:48
	ds_read_b128 v[82:85], v9 offset:64
	ds_read_b128 v[86:89], v9 offset:80
	ds_read_b128 v[90:93], v9 offset:96
	ds_read_b128 v[94:97], v9 offset:112
	global_load_dwordx4 v[130:133], v[6:7], off offset:128
	global_load_dwordx4 v[134:137], v[6:7], off offset:144
	global_load_dwordx4 v[138:141], v[6:7], off offset:160
	global_load_dwordx4 v[142:145], v[6:7], off offset:176
	ds_read_b128 v[98:101], v9 offset:128
	ds_read_b128 v[102:105], v9 offset:144
	ds_read_b128 v[106:109], v9 offset:160
	ds_read_b128 v[110:113], v9 offset:176
	ds_read_b128 v[114:117], v9 offset:192
	ds_read_b128 v[118:121], v9 offset:208
	ds_read_b128 v[122:125], v9 offset:224
	ds_read_b128 v[126:129], v9 offset:240
	s_waitcnt vmcnt(8)
	s_waitcnt lgkmcnt(8)
	v_lshlrev_b32_e32 v36, 16, v20
	v_and_b32_e32 v37, 0xffff0000, v20
	v_lshlrev_b32_e32 v38, 16, v21
	v_mfma_f32_16x16x4_f32 v[12:15], v36, v66, v[12:15]
	v_and_b32_e32 v39, 0xffff0000, v21
	v_mfma_f32_16x16x4_f32 v[16:19], v37, v67, v[16:19]
	v_lshlrev_b32_e32 v36, 16, v22
	v_mfma_f32_16x16x4_f32 v[12:15], v38, v68, v[12:15]
	v_and_b32_e32 v37, 0xffff0000, v22
	v_mfma_f32_16x16x4_f32 v[16:19], v39, v69, v[16:19]
	v_lshlrev_b32_e32 v38, 16, v23
	v_mfma_f32_16x16x4_f32 v[12:15], v36, v70, v[12:15]
	v_and_b32_e32 v39, 0xffff0000, v23
	v_mfma_f32_16x16x4_f32 v[16:19], v37, v71, v[16:19]
	v_lshlrev_b32_e32 v36, 16, v24
	v_mfma_f32_16x16x4_f32 v[12:15], v38, v72, v[12:15]
	v_and_b32_e32 v37, 0xffff0000, v24
	v_mfma_f32_16x16x4_f32 v[16:19], v39, v73, v[16:19]
	v_lshlrev_b32_e32 v38, 16, v25
	v_mfma_f32_16x16x4_f32 v[12:15], v36, v74, v[12:15]
	v_and_b32_e32 v39, 0xffff0000, v25
	v_mfma_f32_16x16x4_f32 v[16:19], v37, v75, v[16:19]
	v_lshlrev_b32_e32 v36, 16, v26
	v_mfma_f32_16x16x4_f32 v[12:15], v38, v76, v[12:15]
	v_and_b32_e32 v37, 0xffff0000, v26
	v_mfma_f32_16x16x4_f32 v[16:19], v39, v77, v[16:19]
	v_lshlrev_b32_e32 v38, 16, v27
	v_mfma_f32_16x16x4_f32 v[12:15], v36, v78, v[12:15]
	v_and_b32_e32 v39, 0xffff0000, v27
	v_mfma_f32_16x16x4_f32 v[16:19], v37, v79, v[16:19]
	v_lshlrev_b32_e32 v36, 16, v28
	v_mfma_f32_16x16x4_f32 v[12:15], v38, v80, v[12:15]
	v_and_b32_e32 v37, 0xffff0000, v28
	v_mfma_f32_16x16x4_f32 v[16:19], v39, v81, v[16:19]
	v_lshlrev_b32_e32 v38, 16, v29
	v_mfma_f32_16x16x4_f32 v[12:15], v36, v82, v[12:15]
	v_and_b32_e32 v39, 0xffff0000, v29
	v_mfma_f32_16x16x4_f32 v[16:19], v37, v83, v[16:19]
	v_lshlrev_b32_e32 v36, 16, v30
	v_mfma_f32_16x16x4_f32 v[12:15], v38, v84, v[12:15]
	v_and_b32_e32 v37, 0xffff0000, v30
	v_mfma_f32_16x16x4_f32 v[16:19], v39, v85, v[16:19]
	v_lshlrev_b32_e32 v38, 16, v31
	v_mfma_f32_16x16x4_f32 v[12:15], v36, v86, v[12:15]
	v_and_b32_e32 v39, 0xffff0000, v31
	v_mfma_f32_16x16x4_f32 v[16:19], v37, v87, v[16:19]
	v_lshlrev_b32_e32 v36, 16, v32
	v_mfma_f32_16x16x4_f32 v[12:15], v38, v88, v[12:15]
	v_and_b32_e32 v37, 0xffff0000, v32
	v_mfma_f32_16x16x4_f32 v[16:19], v39, v89, v[16:19]
	v_lshlrev_b32_e32 v38, 16, v33
	v_mfma_f32_16x16x4_f32 v[12:15], v36, v90, v[12:15]
	v_and_b32_e32 v39, 0xffff0000, v33
	v_mfma_f32_16x16x4_f32 v[16:19], v37, v91, v[16:19]
	v_lshlrev_b32_e32 v36, 16, v34
	v_mfma_f32_16x16x4_f32 v[12:15], v38, v92, v[12:15]
	v_and_b32_e32 v37, 0xffff0000, v34
	v_mfma_f32_16x16x4_f32 v[16:19], v39, v93, v[16:19]
	v_lshlrev_b32_e32 v38, 16, v35
	v_mfma_f32_16x16x4_f32 v[12:15], v36, v94, v[12:15]
	v_and_b32_e32 v39, 0xffff0000, v35
	v_mfma_f32_16x16x4_f32 v[16:19], v37, v95, v[16:19]
	s_nop 0
	v_mfma_f32_16x16x4_f32 v[12:15], v38, v96, v[12:15]
	s_nop 0
	v_mfma_f32_16x16x4_f32 v[16:19], v39, v97, v[16:19]
	global_load_dwordx4 v[20:23], v[6:7], off offset:192
	global_load_dwordx4 v[24:27], v[6:7], off offset:208
	global_load_dwordx4 v[28:31], v[6:7], off offset:224
	global_load_dwordx4 v[32:35], v[6:7], off offset:240
	ds_read_b128 v[66:69], v9 offset:256
	ds_read_b128 v[70:73], v9 offset:272
	ds_read_b128 v[74:77], v9 offset:288
	ds_read_b128 v[78:81], v9 offset:304
	ds_read_b128 v[82:85], v9 offset:320
	ds_read_b128 v[86:89], v9 offset:336
	ds_read_b128 v[90:93], v9 offset:352
	ds_read_b128 v[94:97], v9 offset:368
	s_waitcnt vmcnt(8)
; template <int NS>
; DI_ void skinny_pass_bf16(const bf16_t* XBrows, int nrows, const float* WsT, float* sk_out, int gw, int NGW, int lane) {
;     ...
;         for (int grp = 0; grp < NS / 8; ++grp) {
;             float a[4][8];
; #pragma unroll
;             for (int jc = 0; jc < 8; ++jc) {
;                 const float* wp = WsT + (8 * grp + jc) * WST + 4 * lane; float s0 = 0.f, s1 = 0.f, s2 = 0.f, s3 = 0.f;
; #pragma unroll
;                 for (int j = 0; j < 4; ++j) { const f32x4 w = *(const f32x4*)(wp + 256 * j);
;                     s0 += (v[0][4 * j] * w[0] + v[0][4 * j + 1] * w[1]) + (v[0][4 * j + 2] * w[2] + v[0][4 * j + 3] * w[3]);
;                     s1 += (v[1][4 * j] * w[0] + v[1][4 * j + 1] * w[1]) + (v[1][4 * j + 2] * w[2] + v[1][4 * j + 3] * w[3]);
;                     s2 += (v[2][4 * j] * w[0] + v[2][4 * j + 1] * w[1]) + (v[2][4 * j + 2] * w[2] + v[2][4 * j + 3] * w[3]);
;                     s3 += (v[3][4 * j] * w[0] + v[3][4 * j + 1] * w[1]) + (v[3][4 * j + 2] * w[2] + v[3][4 * j + 3] * w[3]); }
;                 a[0][jc] = s0; a[1][jc] = s1; a[2][jc] = s2; a[3][jc] = s3;
	s_waitcnt lgkmcnt(8)
	v_lshlrev_b32_e32 v36, 16, v50
	v_and_b32_e32 v37, 0xffff0000, v50
	v_lshlrev_b32_e32 v38, 16, v51
	v_mfma_f32_16x16x4_f32 v[12:15], v36, v98, v[12:15]
	v_and_b32_e32 v39, 0xffff0000, v51
	v_mfma_f32_16x16x4_f32 v[16:19], v37, v99, v[16:19]
	v_lshlrev_b32_e32 v36, 16, v52
	v_mfma_f32_16x16x4_f32 v[12:15], v38, v100, v[12:15]
	v_and_b32_e32 v37, 0xffff0000, v52
	v_mfma_f32_16x16x4_f32 v[16:19], v39, v101, v[16:19]
	v_lshlrev_b32_e32 v38, 16, v53
	v_mfma_f32_16x16x4_f32 v[12:15], v36, v102, v[12:15]
	v_and_b32_e32 v39, 0xffff0000, v53
	v_mfma_f32_16x16x4_f32 v[16:19], v37, v103, v[16:19]
	v_lshlrev_b32_e32 v36, 16, v54
	v_mfma_f32_16x16x4_f32 v[12:15], v38, v104, v[12:15]
	v_and_b32_e32 v37, 0xffff0000, v54
	v_mfma_f32_16x16x4_f32 v[16:19], v39, v105, v[16:19]
	v_lshlrev_b32_e32 v38, 16, v55
	v_mfma_f32_16x16x4_f32 v[12:15], v36, v106, v[12:15]
	v_and_b32_e32 v39, 0xffff0000, v55
	v_mfma_f32_16x16x4_f32 v[16:19], v37, v107, v[16:19]
	v_lshlrev_b32_e32 v36, 16, v56
	v_mfma_f32_16x16x4_f32 v[12:15], v38, v108, v[12:15]
	v_and_b32_e32 v37, 0xffff0000, v56
	v_mfma_f32_16x16x4_f32 v[16:19], v39, v109, v[16:19]
	v_lshlrev_b32_e32 v38, 16, v57
	v_mfma_f32_16x16x4_f32 v[12:15], v36, v110, v[12:15]
	v_and_b32_e32 v39, 0xffff0000, v57
	v_mfma_f32_16x16x4_f32 v[16:19], v37, v111, v[16:19]
	v_lshlrev_b32_e32 v36, 16, v58
	v_mfma_f32_16x16x4_f32 v[12:15], v38, v112, v[12:15]
	v_and_b32_e32 v37, 0xffff0000, v58
	v_mfma_f32_16x16x4_f32 v[16:19], v39, v113, v[16:19]
	v_lshlrev_b32_e32 v38, 16, v59
	v_mfma_f32_16x16x4_f32 v[12:15], v36, v114, v[12:15]
	v_and_b32_e32 v39, 0xffff0000, v59
	v_mfma_f32_16x16x4_f32 v[16:19], v37, v115, v[16:19]
	v_lshlrev_b32_e32 v36, 16, v60
	v_mfma_f32_16x16x4_f32 v[12:15], v38, v116, v[12:15]
	v_and_b32_e32 v37, 0xffff0000, v60
	v_mfma_f32_16x16x4_f32 v[16:19], v39, v117, v[16:19]
	v_lshlrev_b32_e32 v38, 16, v61
	v_mfma_f32_16x16x4_f32 v[12:15], v36, v118, v[12:15]
	v_and_b32_e32 v39, 0xffff0000, v61
	v_mfma_f32_16x16x4_f32 v[16:19], v37, v119, v[16:19]
	v_lshlrev_b32_e32 v36, 16, v62
	v_mfma_f32_16x16x4_f32 v[12:15], v38, v120, v[12:15]
	v_and_b32_e32 v37, 0xffff0000, v62
	v_mfma_f32_16x16x4_f32 v[16:19], v39, v121, v[16:19]
	v_lshlrev_b32_e32 v38, 16, v63
	v_mfma_f32_16x16x4_f32 v[12:15], v36, v122, v[12:15]
	v_and_b32_e32 v39, 0xffff0000, v63
	v_mfma_f32_16x16x4_f32 v[16:19], v37, v123, v[16:19]
	v_lshlrev_b32_e32 v36, 16, v64
	v_mfma_f32_16x16x4_f32 v[12:15], v38, v124, v[12:15]
	v_and_b32_e32 v37, 0xffff0000, v64
	v_mfma_f32_16x16x4_f32 v[16:19], v39, v125, v[16:19]
	v_lshlrev_b32_e32 v38, 16, v65
	v_mfma_f32_16x16x4_f32 v[12:15], v36, v126, v[12:15]
	v_and_b32_e32 v39, 0xffff0000, v65
	v_mfma_f32_16x16x4_f32 v[16:19], v37, v127, v[16:19]
	s_nop 0
	v_mfma_f32_16x16x4_f32 v[12:15], v38, v128, v[12:15]
	s_nop 0
	v_mfma_f32_16x16x4_f32 v[16:19], v39, v129, v[16:19]
	global_load_dwordx4 v[50:53], v[6:7], off offset:256
	global_load_dwordx4 v[54:57], v[6:7], off offset:272
	global_load_dwordx4 v[58:61], v[6:7], off offset:288
	global_load_dwordx4 v[62:65], v[6:7], off offset:304
	ds_read_b128 v[98:101], v9 offset:384
	ds_read_b128 v[102:105], v9 offset:400
	ds_read_b128 v[106:109], v9 offset:416
	ds_read_b128 v[110:113], v9 offset:432
	ds_read_b128 v[114:117], v9 offset:448
	ds_read_b128 v[118:121], v9 offset:464
	ds_read_b128 v[122:125], v9 offset:480
	ds_read_b128 v[126:129], v9 offset:496
	s_waitcnt vmcnt(8)
	s_waitcnt lgkmcnt(8)
	v_lshlrev_b32_e32 v36, 16, v130
	v_and_b32_e32 v37, 0xffff0000, v130
	v_lshlrev_b32_e32 v38, 16, v131
	v_mfma_f32_16x16x4_f32 v[12:15], v36, v66, v[12:15]
	v_and_b32_e32 v39, 0xffff0000, v131
	v_mfma_f32_16x16x4_f32 v[16:19], v37, v67, v[16:19]
	v_lshlrev_b32_e32 v36, 16, v132
	v_mfma_f32_16x16x4_f32 v[12:15], v38, v68, v[12:15]
	v_and_b32_e32 v37, 0xffff0000, v132
	v_mfma_f32_16x16x4_f32 v[16:19], v39, v69, v[16:19]
	v_lshlrev_b32_e32 v38, 16, v133
	v_mfma_f32_16x16x4_f32 v[12:15], v36, v70, v[12:15]
	v_and_b32_e32 v39, 0xffff0000, v133
	v_mfma_f32_16x16x4_f32 v[16:19], v37, v71, v[16:19]
	v_lshlrev_b32_e32 v36, 16, v134
	v_mfma_f32_16x16x4_f32 v[12:15], v38, v72, v[12:15]
	v_and_b32_e32 v37, 0xffff0000, v134
	v_mfma_f32_16x16x4_f32 v[16:19], v39, v73, v[16:19]
	v_lshlrev_b32_e32 v38, 16, v135
	v_mfma_f32_16x16x4_f32 v[12:15], v36, v74, v[12:15]
	v_and_b32_e32 v39, 0xffff0000, v135
	v_mfma_f32_16x16x4_f32 v[16:19], v37, v75, v[16:19]
	v_lshlrev_b32_e32 v36, 16, v136
	v_mfma_f32_16x16x4_f32 v[12:15], v38, v76, v[12:15]
	v_and_b32_e32 v37, 0xffff0000, v136
	v_mfma_f32_16x16x4_f32 v[16:19], v39, v77, v[16:19]
	v_lshlrev_b32_e32 v38, 16, v137
	v_mfma_f32_16x16x4_f32 v[12:15], v36, v78, v[12:15]
	v_and_b32_e32 v39, 0xffff0000, v137
	v_mfma_f32_16x16x4_f32 v[16:19], v37, v79, v[16:19]
	v_lshlrev_b32_e32 v36, 16, v138
	v_mfma_f32_16x16x4_f32 v[12:15], v38, v80, v[12:15]
	v_and_b32_e32 v37, 0xffff0000, v138
	v_mfma_f32_16x16x4_f32 v[16:19], v39, v81, v[16:19]
	v_lshlrev_b32_e32 v38, 16, v139
	v_mfma_f32_16x16x4_f32 v[12:15], v36, v82, v[12:15]
	v_and_b32_e32 v39, 0xffff0000, v139
	v_mfma_f32_16x16x4_f32 v[16:19], v37, v83, v[16:19]
	v_lshlrev_b32_e32 v36, 16, v140
	v_mfma_f32_16x16x4_f32 v[12:15], v38, v84, v[12:15]
	v_and_b32_e32 v37, 0xffff0000, v140
	v_mfma_f32_16x16x4_f32 v[16:19], v39, v85, v[16:19]
	v_lshlrev_b32_e32 v38, 16, v141
	v_mfma_f32_16x16x4_f32 v[12:15], v36, v86, v[12:15]
	v_and_b32_e32 v39, 0xffff0000, v141
	v_mfma_f32_16x16x4_f32 v[16:19], v37, v87, v[16:19]
	v_lshlrev_b32_e32 v36, 16, v142
	v_mfma_f32_16x16x4_f32 v[12:15], v38, v88, v[12:15]
	v_and_b32_e32 v37, 0xffff0000, v142
	v_mfma_f32_16x16x4_f32 v[16:19], v39, v89, v[16:19]
	v_lshlrev_b32_e32 v38, 16, v143
	v_mfma_f32_16x16x4_f32 v[12:15], v36, v90, v[12:15]
	v_and_b32_e32 v39, 0xffff0000, v143
	v_mfma_f32_16x16x4_f32 v[16:19], v37, v91, v[16:19]
	v_lshlrev_b32_e32 v36, 16, v144
	v_mfma_f32_16x16x4_f32 v[12:15], v38, v92, v[12:15]
	v_and_b32_e32 v37, 0xffff0000, v144
	v_mfma_f32_16x16x4_f32 v[16:19], v39, v93, v[16:19]
	v_lshlrev_b32_e32 v38, 16, v145
	v_mfma_f32_16x16x4_f32 v[12:15], v36, v94, v[12:15]
	v_and_b32_e32 v39, 0xffff0000, v145
	v_mfma_f32_16x16x4_f32 v[16:19], v37, v95, v[16:19]
	s_nop 0
	v_mfma_f32_16x16x4_f32 v[12:15], v38, v96, v[12:15]
	s_nop 0
	v_mfma_f32_16x16x4_f32 v[16:19], v39, v97, v[16:19]
	global_load_dwordx4 v[130:133], v[6:7], off offset:320
	global_load_dwordx4 v[134:137], v[6:7], off offset:336
	global_load_dwordx4 v[138:141], v[6:7], off offset:352
	global_load_dwordx4 v[142:145], v[6:7], off offset:368
	ds_read_b128 v[66:69], v9 offset:512
	ds_read_b128 v[70:73], v9 offset:528
	ds_read_b128 v[74:77], v9 offset:544
	ds_read_b128 v[78:81], v9 offset:560
	ds_read_b128 v[82:85], v9 offset:576
	ds_read_b128 v[86:89], v9 offset:592
	ds_read_b128 v[90:93], v9 offset:608
	ds_read_b128 v[94:97], v9 offset:624
	s_waitcnt vmcnt(8)
; template <int NS>
; DI_ void skinny_pass_bf16(const bf16_t* XBrows, int nrows, const float* WsT, float* sk_out, int gw, int NGW, int lane) {
;     ...
;         for (int grp = 0; grp < NS / 8; ++grp) {
;             float a[4][8];
; #pragma unroll
;             for (int jc = 0; jc < 8; ++jc) {
;                 const float* wp = WsT + (8 * grp + jc) * WST + 4 * lane; float s0 = 0.f, s1 = 0.f, s2 = 0.f, s3 = 0.f;
; #pragma unroll
;                 for (int j = 0; j < 4; ++j) { const f32x4 w = *(const f32x4*)(wp + 256 * j);
;                     s0 += (v[0][4 * j] * w[0] + v[0][4 * j + 1] * w[1]) + (v[0][4 * j + 2] * w[2] + v[0][4 * j + 3] * w[3]);
;                     s1 += (v[1][4 * j] * w[0] + v[1][4 * j + 1] * w[1]) + (v[1][4 * j + 2] * w[2] + v[1][4 * j + 3] * w[3]);
;                     s2 += (v[2][4 * j] * w[0] + v[2][4 * j + 1] * w[1]) + (v[2][4 * j + 2] * w[2] + v[2][4 * j + 3] * w[3]);
;                     s3 += (v[3][4 * j] * w[0] + v[3][4 * j + 1] * w[1]) + (v[3][4 * j + 2] * w[2] + v[3][4 * j + 3] * w[3]); }
;                 a[0][jc] = s0; a[1][jc] = s1; a[2][jc] = s2; a[3][jc] = s3;
	s_waitcnt lgkmcnt(8)
	v_lshlrev_b32_e32 v36, 16, v20
	v_and_b32_e32 v37, 0xffff0000, v20
	v_lshlrev_b32_e32 v38, 16, v21
	v_mfma_f32_16x16x4_f32 v[12:15], v36, v98, v[12:15]
	v_and_b32_e32 v39, 0xffff0000, v21
	v_mfma_f32_16x16x4_f32 v[16:19], v37, v99, v[16:19]
	v_lshlrev_b32_e32 v36, 16, v22
	v_mfma_f32_16x16x4_f32 v[12:15], v38, v100, v[12:15]
	v_and_b32_e32 v37, 0xffff0000, v22
	v_mfma_f32_16x16x4_f32 v[16:19], v39, v101, v[16:19]
	v_lshlrev_b32_e32 v38, 16, v23
	v_mfma_f32_16x16x4_f32 v[12:15], v36, v102, v[12:15]
	v_and_b32_e32 v39, 0xffff0000, v23
	v_mfma_f32_16x16x4_f32 v[16:19], v37, v103, v[16:19]
	v_lshlrev_b32_e32 v36, 16, v24
	v_mfma_f32_16x16x4_f32 v[12:15], v38, v104, v[12:15]
	v_and_b32_e32 v37, 0xffff0000, v24
	v_mfma_f32_16x16x4_f32 v[16:19], v39, v105, v[16:19]
	v_lshlrev_b32_e32 v38, 16, v25
	v_mfma_f32_16x16x4_f32 v[12:15], v36, v106, v[12:15]
	v_and_b32_e32 v39, 0xffff0000, v25
	v_mfma_f32_16x16x4_f32 v[16:19], v37, v107, v[16:19]
	v_lshlrev_b32_e32 v36, 16, v26
	v_mfma_f32_16x16x4_f32 v[12:15], v38, v108, v[12:15]
	v_and_b32_e32 v37, 0xffff0000, v26
	v_mfma_f32_16x16x4_f32 v[16:19], v39, v109, v[16:19]
	v_lshlrev_b32_e32 v38, 16, v27
	v_mfma_f32_16x16x4_f32 v[12:15], v36, v110, v[12:15]
	v_and_b32_e32 v39, 0xffff0000, v27
	v_mfma_f32_16x16x4_f32 v[16:19], v37, v111, v[16:19]
	v_lshlrev_b32_e32 v36, 16, v28
	v_mfma_f32_16x16x4_f32 v[12:15], v38, v112, v[12:15]
	v_and_b32_e32 v37, 0xffff0000, v28
	v_mfma_f32_16x16x4_f32 v[16:19], v39, v113, v[16:19]
	v_lshlrev_b32_e32 v38, 16, v29
	v_mfma_f32_16x16x4_f32 v[12:15], v36, v114, v[12:15]
	v_and_b32_e32 v39, 0xffff0000, v29
	v_mfma_f32_16x16x4_f32 v[16:19], v37, v115, v[16:19]
	v_lshlrev_b32_e32 v36, 16, v30
	v_mfma_f32_16x16x4_f32 v[12:15], v38, v116, v[12:15]
	v_and_b32_e32 v37, 0xffff0000, v30
	v_mfma_f32_16x16x4_f32 v[16:19], v39, v117, v[16:19]
	v_lshlrev_b32_e32 v38, 16, v31
	v_mfma_f32_16x16x4_f32 v[12:15], v36, v118, v[12:15]
	v_and_b32_e32 v39, 0xffff0000, v31
	v_mfma_f32_16x16x4_f32 v[16:19], v37, v119, v[16:19]
	v_lshlrev_b32_e32 v36, 16, v32
	v_mfma_f32_16x16x4_f32 v[12:15], v38, v120, v[12:15]
	v_and_b32_e32 v37, 0xffff0000, v32
	v_mfma_f32_16x16x4_f32 v[16:19], v39, v121, v[16:19]
	v_lshlrev_b32_e32 v38, 16, v33
	v_mfma_f32_16x16x4_f32 v[12:15], v36, v122, v[12:15]
	v_and_b32_e32 v39, 0xffff0000, v33
	v_mfma_f32_16x16x4_f32 v[16:19], v37, v123, v[16:19]
	v_lshlrev_b32_e32 v36, 16, v34
	v_mfma_f32_16x16x4_f32 v[12:15], v38, v124, v[12:15]
	v_and_b32_e32 v37, 0xffff0000, v34
	v_mfma_f32_16x16x4_f32 v[16:19], v39, v125, v[16:19]
	v_lshlrev_b32_e32 v38, 16, v35
	v_mfma_f32_16x16x4_f32 v[12:15], v36, v126, v[12:15]
	v_and_b32_e32 v39, 0xffff0000, v35
	v_mfma_f32_16x16x4_f32 v[16:19], v37, v127, v[16:19]
	s_nop 0
	v_mfma_f32_16x16x4_f32 v[12:15], v38, v128, v[12:15]
	s_nop 0
	v_mfma_f32_16x16x4_f32 v[16:19], v39, v129, v[16:19]
	global_load_dwordx4 v[20:23], v[6:7], off offset:384
	global_load_dwordx4 v[24:27], v[6:7], off offset:400
	global_load_dwordx4 v[28:31], v[6:7], off offset:416
	global_load_dwordx4 v[32:35], v[6:7], off offset:432
	ds_read_b128 v[98:101], v9 offset:640
	ds_read_b128 v[102:105], v9 offset:656
	ds_read_b128 v[106:109], v9 offset:672
	ds_read_b128 v[110:113], v9 offset:688
	ds_read_b128 v[114:117], v9 offset:704
	ds_read_b128 v[118:121], v9 offset:720
	ds_read_b128 v[122:125], v9 offset:736
	ds_read_b128 v[126:129], v9 offset:752
	s_waitcnt vmcnt(8)
	s_waitcnt lgkmcnt(8)
	v_lshlrev_b32_e32 v36, 16, v50
	v_and_b32_e32 v37, 0xffff0000, v50
	v_lshlrev_b32_e32 v38, 16, v51
	v_mfma_f32_16x16x4_f32 v[12:15], v36, v66, v[12:15]
	v_and_b32_e32 v39, 0xffff0000, v51
	v_mfma_f32_16x16x4_f32 v[16:19], v37, v67, v[16:19]
	v_lshlrev_b32_e32 v36, 16, v52
	v_mfma_f32_16x16x4_f32 v[12:15], v38, v68, v[12:15]
	v_and_b32_e32 v37, 0xffff0000, v52
	v_mfma_f32_16x16x4_f32 v[16:19], v39, v69, v[16:19]
	v_lshlrev_b32_e32 v38, 16, v53
	v_mfma_f32_16x16x4_f32 v[12:15], v36, v70, v[12:15]
	v_and_b32_e32 v39, 0xffff0000, v53
	v_mfma_f32_16x16x4_f32 v[16:19], v37, v71, v[16:19]
	v_lshlrev_b32_e32 v36, 16, v54
	v_mfma_f32_16x16x4_f32 v[12:15], v38, v72, v[12:15]
	v_and_b32_e32 v37, 0xffff0000, v54
	v_mfma_f32_16x16x4_f32 v[16:19], v39, v73, v[16:19]
	v_lshlrev_b32_e32 v38, 16, v55
	v_mfma_f32_16x16x4_f32 v[12:15], v36, v74, v[12:15]
	v_and_b32_e32 v39, 0xffff0000, v55
	v_mfma_f32_16x16x4_f32 v[16:19], v37, v75, v[16:19]
	v_lshlrev_b32_e32 v36, 16, v56
	v_mfma_f32_16x16x4_f32 v[12:15], v38, v76, v[12:15]
	v_and_b32_e32 v37, 0xffff0000, v56
	v_mfma_f32_16x16x4_f32 v[16:19], v39, v77, v[16:19]
	v_lshlrev_b32_e32 v38, 16, v57
	v_mfma_f32_16x16x4_f32 v[12:15], v36, v78, v[12:15]
	v_and_b32_e32 v39, 0xffff0000, v57
	v_mfma_f32_16x16x4_f32 v[16:19], v37, v79, v[16:19]
	v_lshlrev_b32_e32 v36, 16, v58
	v_mfma_f32_16x16x4_f32 v[12:15], v38, v80, v[12:15]
	v_and_b32_e32 v37, 0xffff0000, v58
	v_mfma_f32_16x16x4_f32 v[16:19], v39, v81, v[16:19]
	v_lshlrev_b32_e32 v38, 16, v59
	v_mfma_f32_16x16x4_f32 v[12:15], v36, v82, v[12:15]
	v_and_b32_e32 v39, 0xffff0000, v59
	v_mfma_f32_16x16x4_f32 v[16:19], v37, v83, v[16:19]
	v_lshlrev_b32_e32 v36, 16, v60
	v_mfma_f32_16x16x4_f32 v[12:15], v38, v84, v[12:15]
	v_and_b32_e32 v37, 0xffff0000, v60
	v_mfma_f32_16x16x4_f32 v[16:19], v39, v85, v[16:19]
	v_lshlrev_b32_e32 v38, 16, v61
	v_mfma_f32_16x16x4_f32 v[12:15], v36, v86, v[12:15]
	v_and_b32_e32 v39, 0xffff0000, v61
	v_mfma_f32_16x16x4_f32 v[16:19], v37, v87, v[16:19]
	v_lshlrev_b32_e32 v36, 16, v62
	v_mfma_f32_16x16x4_f32 v[12:15], v38, v88, v[12:15]
	v_and_b32_e32 v37, 0xffff0000, v62
	v_mfma_f32_16x16x4_f32 v[16:19], v39, v89, v[16:19]
	v_lshlrev_b32_e32 v38, 16, v63
	v_mfma_f32_16x16x4_f32 v[12:15], v36, v90, v[12:15]
	v_and_b32_e32 v39, 0xffff0000, v63
	v_mfma_f32_16x16x4_f32 v[16:19], v37, v91, v[16:19]
	v_lshlrev_b32_e32 v36, 16, v64
	v_mfma_f32_16x16x4_f32 v[12:15], v38, v92, v[12:15]
	v_and_b32_e32 v37, 0xffff0000, v64
	v_mfma_f32_16x16x4_f32 v[16:19], v39, v93, v[16:19]
	v_lshlrev_b32_e32 v38, 16, v65
	v_mfma_f32_16x16x4_f32 v[12:15], v36, v94, v[12:15]
	v_and_b32_e32 v39, 0xffff0000, v65
	v_mfma_f32_16x16x4_f32 v[16:19], v37, v95, v[16:19]
	s_nop 0
	v_mfma_f32_16x16x4_f32 v[12:15], v38, v96, v[12:15]
	s_nop 0
	v_mfma_f32_16x16x4_f32 v[16:19], v39, v97, v[16:19]
	global_load_dwordx4 v[50:53], v[6:7], off offset:448
	global_load_dwordx4 v[54:57], v[6:7], off offset:464
	global_load_dwordx4 v[58:61], v[6:7], off offset:480
	global_load_dwordx4 v[62:65], v[6:7], off offset:496
	ds_read_b128 v[66:69], v9 offset:768
	ds_read_b128 v[70:73], v9 offset:784
	ds_read_b128 v[74:77], v9 offset:800
	ds_read_b128 v[78:81], v9 offset:816
	ds_read_b128 v[82:85], v9 offset:832
	ds_read_b128 v[86:89], v9 offset:848
	ds_read_b128 v[90:93], v9 offset:864
	ds_read_b128 v[94:97], v9 offset:880
	s_waitcnt vmcnt(8)
; template <int NS>
; DI_ void skinny_pass_bf16(const bf16_t* XBrows, int nrows, const float* WsT, float* sk_out, int gw, int NGW, int lane) {
;     ...
;         for (int grp = 0; grp < NS / 8; ++grp) {
;             float a[4][8];
; #pragma unroll
;             for (int jc = 0; jc < 8; ++jc) {
;                 const float* wp = WsT + (8 * grp + jc) * WST + 4 * lane; float s0 = 0.f, s1 = 0.f, s2 = 0.f, s3 = 0.f;
; #pragma unroll
;                 for (int j = 0; j < 4; ++j) { const f32x4 w = *(const f32x4*)(wp + 256 * j);
;                     s0 += (v[0][4 * j] * w[0] + v[0][4 * j + 1] * w[1]) + (v[0][4 * j + 2] * w[2] + v[0][4 * j + 3] * w[3]);
;                     s1 += (v[1][4 * j] * w[0] + v[1][4 * j + 1] * w[1]) + (v[1][4 * j + 2] * w[2] + v[1][4 * j + 3] * w[3]);
;                     s2 += (v[2][4 * j] * w[0] + v[2][4 * j + 1] * w[1]) + (v[2][4 * j + 2] * w[2] + v[2][4 * j + 3] * w[3]);
;                     s3 += (v[3][4 * j] * w[0] + v[3][4 * j + 1] * w[1]) + (v[3][4 * j + 2] * w[2] + v[3][4 * j + 3] * w[3]); }
;                 a[0][jc] = s0; a[1][jc] = s1; a[2][jc] = s2; a[3][jc] = s3;
	s_waitcnt lgkmcnt(8)
	v_lshlrev_b32_e32 v36, 16, v130
	v_and_b32_e32 v37, 0xffff0000, v130
	v_lshlrev_b32_e32 v38, 16, v131
	v_mfma_f32_16x16x4_f32 v[12:15], v36, v98, v[12:15]
	v_and_b32_e32 v39, 0xffff0000, v131
	v_mfma_f32_16x16x4_f32 v[16:19], v37, v99, v[16:19]
	v_lshlrev_b32_e32 v36, 16, v132
	v_mfma_f32_16x16x4_f32 v[12:15], v38, v100, v[12:15]
	v_and_b32_e32 v37, 0xffff0000, v132
	v_mfma_f32_16x16x4_f32 v[16:19], v39, v101, v[16:19]
	v_lshlrev_b32_e32 v38, 16, v133
	v_mfma_f32_16x16x4_f32 v[12:15], v36, v102, v[12:15]
	v_and_b32_e32 v39, 0xffff0000, v133
	v_mfma_f32_16x16x4_f32 v[16:19], v37, v103, v[16:19]
	v_lshlrev_b32_e32 v36, 16, v134
	v_mfma_f32_16x16x4_f32 v[12:15], v38, v104, v[12:15]
	v_and_b32_e32 v37, 0xffff0000, v134
	v_mfma_f32_16x16x4_f32 v[16:19], v39, v105, v[16:19]
	v_lshlrev_b32_e32 v38, 16, v135
	v_mfma_f32_16x16x4_f32 v[12:15], v36, v106, v[12:15]
	v_and_b32_e32 v39, 0xffff0000, v135
	v_mfma_f32_16x16x4_f32 v[16:19], v37, v107, v[16:19]
	v_lshlrev_b32_e32 v36, 16, v136
	v_mfma_f32_16x16x4_f32 v[12:15], v38, v108, v[12:15]
	v_and_b32_e32 v37, 0xffff0000, v136
	v_mfma_f32_16x16x4_f32 v[16:19], v39, v109, v[16:19]
	v_lshlrev_b32_e32 v38, 16, v137
	v_mfma_f32_16x16x4_f32 v[12:15], v36, v110, v[12:15]
	v_and_b32_e32 v39, 0xffff0000, v137
	v_mfma_f32_16x16x4_f32 v[16:19], v37, v111, v[16:19]
	v_lshlrev_b32_e32 v36, 16, v138
	v_mfma_f32_16x16x4_f32 v[12:15], v38, v112, v[12:15]
	v_and_b32_e32 v37, 0xffff0000, v138
	v_mfma_f32_16x16x4_f32 v[16:19], v39, v113, v[16:19]
	v_lshlrev_b32_e32 v38, 16, v139
	v_mfma_f32_16x16x4_f32 v[12:15], v36, v114, v[12:15]
	v_and_b32_e32 v39, 0xffff0000, v139
	v_mfma_f32_16x16x4_f32 v[16:19], v37, v115, v[16:19]
	v_lshlrev_b32_e32 v36, 16, v140
	v_mfma_f32_16x16x4_f32 v[12:15], v38, v116, v[12:15]
	v_and_b32_e32 v37, 0xffff0000, v140
	v_mfma_f32_16x16x4_f32 v[16:19], v39, v117, v[16:19]
	v_lshlrev_b32_e32 v38, 16, v141
	v_mfma_f32_16x16x4_f32 v[12:15], v36, v118, v[12:15]
	v_and_b32_e32 v39, 0xffff0000, v141
	v_mfma_f32_16x16x4_f32 v[16:19], v37, v119, v[16:19]
	v_lshlrev_b32_e32 v36, 16, v142
	v_mfma_f32_16x16x4_f32 v[12:15], v38, v120, v[12:15]
	v_and_b32_e32 v37, 0xffff0000, v142
	v_mfma_f32_16x16x4_f32 v[16:19], v39, v121, v[16:19]
	v_lshlrev_b32_e32 v38, 16, v143
	v_mfma_f32_16x16x4_f32 v[12:15], v36, v122, v[12:15]
	v_and_b32_e32 v39, 0xffff0000, v143
	v_mfma_f32_16x16x4_f32 v[16:19], v37, v123, v[16:19]
	v_lshlrev_b32_e32 v36, 16, v144
	v_mfma_f32_16x16x4_f32 v[12:15], v38, v124, v[12:15]
	v_and_b32_e32 v37, 0xffff0000, v144
	v_mfma_f32_16x16x4_f32 v[16:19], v39, v125, v[16:19]
	v_lshlrev_b32_e32 v38, 16, v145
	v_mfma_f32_16x16x4_f32 v[12:15], v36, v126, v[12:15]
	v_and_b32_e32 v39, 0xffff0000, v145
	v_mfma_f32_16x16x4_f32 v[16:19], v37, v127, v[16:19]
	s_nop 0
	v_mfma_f32_16x16x4_f32 v[12:15], v38, v128, v[12:15]
	s_nop 0
	v_mfma_f32_16x16x4_f32 v[16:19], v39, v129, v[16:19]
	ds_read_b128 v[98:101], v9 offset:896
	ds_read_b128 v[102:105], v9 offset:912
	ds_read_b128 v[106:109], v9 offset:928
	ds_read_b128 v[110:113], v9 offset:944
	ds_read_b128 v[114:117], v9 offset:960
	ds_read_b128 v[118:121], v9 offset:976
	ds_read_b128 v[122:125], v9 offset:992
	ds_read_b128 v[126:129], v9 offset:1008
	s_waitcnt vmcnt(4)
	s_waitcnt lgkmcnt(8)
	v_lshlrev_b32_e32 v36, 16, v20
	v_and_b32_e32 v37, 0xffff0000, v20
	v_lshlrev_b32_e32 v38, 16, v21
	v_mfma_f32_16x16x4_f32 v[12:15], v36, v66, v[12:15]
	v_and_b32_e32 v39, 0xffff0000, v21
	v_mfma_f32_16x16x4_f32 v[16:19], v37, v67, v[16:19]
	v_lshlrev_b32_e32 v36, 16, v22
	v_mfma_f32_16x16x4_f32 v[12:15], v38, v68, v[12:15]
	v_and_b32_e32 v37, 0xffff0000, v22
	v_mfma_f32_16x16x4_f32 v[16:19], v39, v69, v[16:19]
	v_lshlrev_b32_e32 v38, 16, v23
	v_mfma_f32_16x16x4_f32 v[12:15], v36, v70, v[12:15]
	v_and_b32_e32 v39, 0xffff0000, v23
	v_mfma_f32_16x16x4_f32 v[16:19], v37, v71, v[16:19]
	v_lshlrev_b32_e32 v36, 16, v24
	v_mfma_f32_16x16x4_f32 v[12:15], v38, v72, v[12:15]
	v_and_b32_e32 v37, 0xffff0000, v24
	v_mfma_f32_16x16x4_f32 v[16:19], v39, v73, v[16:19]
	v_lshlrev_b32_e32 v38, 16, v25
	v_mfma_f32_16x16x4_f32 v[12:15], v36, v74, v[12:15]
	v_and_b32_e32 v39, 0xffff0000, v25
	v_mfma_f32_16x16x4_f32 v[16:19], v37, v75, v[16:19]
	v_lshlrev_b32_e32 v36, 16, v26
	v_mfma_f32_16x16x4_f32 v[12:15], v38, v76, v[12:15]
	v_and_b32_e32 v37, 0xffff0000, v26
	v_mfma_f32_16x16x4_f32 v[16:19], v39, v77, v[16:19]
	v_lshlrev_b32_e32 v38, 16, v27
	v_mfma_f32_16x16x4_f32 v[12:15], v36, v78, v[12:15]
	v_and_b32_e32 v39, 0xffff0000, v27
	v_mfma_f32_16x16x4_f32 v[16:19], v37, v79, v[16:19]
	v_lshlrev_b32_e32 v36, 16, v28
	v_mfma_f32_16x16x4_f32 v[12:15], v38, v80, v[12:15]
	v_and_b32_e32 v37, 0xffff0000, v28
	v_mfma_f32_16x16x4_f32 v[16:19], v39, v81, v[16:19]
	v_lshlrev_b32_e32 v38, 16, v29
	v_mfma_f32_16x16x4_f32 v[12:15], v36, v82, v[12:15]
	v_and_b32_e32 v39, 0xffff0000, v29
	v_mfma_f32_16x16x4_f32 v[16:19], v37, v83, v[16:19]
	v_lshlrev_b32_e32 v36, 16, v30
	v_mfma_f32_16x16x4_f32 v[12:15], v38, v84, v[12:15]
	v_and_b32_e32 v37, 0xffff0000, v30
	v_mfma_f32_16x16x4_f32 v[16:19], v39, v85, v[16:19]
	v_lshlrev_b32_e32 v38, 16, v31
	v_mfma_f32_16x16x4_f32 v[12:15], v36, v86, v[12:15]
	v_and_b32_e32 v39, 0xffff0000, v31
	v_mfma_f32_16x16x4_f32 v[16:19], v37, v87, v[16:19]
	v_lshlrev_b32_e32 v36, 16, v32
	v_mfma_f32_16x16x4_f32 v[12:15], v38, v88, v[12:15]
	v_and_b32_e32 v37, 0xffff0000, v32
	v_mfma_f32_16x16x4_f32 v[16:19], v39, v89, v[16:19]
	v_lshlrev_b32_e32 v38, 16, v33
	v_mfma_f32_16x16x4_f32 v[12:15], v36, v90, v[12:15]
	v_and_b32_e32 v39, 0xffff0000, v33
	v_mfma_f32_16x16x4_f32 v[16:19], v37, v91, v[16:19]
	v_lshlrev_b32_e32 v36, 16, v34
	v_mfma_f32_16x16x4_f32 v[12:15], v38, v92, v[12:15]
	v_and_b32_e32 v37, 0xffff0000, v34
	v_mfma_f32_16x16x4_f32 v[16:19], v39, v93, v[16:19]
	v_lshlrev_b32_e32 v38, 16, v35
	v_mfma_f32_16x16x4_f32 v[12:15], v36, v94, v[12:15]
	v_and_b32_e32 v39, 0xffff0000, v35
	v_mfma_f32_16x16x4_f32 v[16:19], v37, v95, v[16:19]
	s_nop 0
	v_mfma_f32_16x16x4_f32 v[12:15], v38, v96, v[12:15]
	s_nop 0
	v_mfma_f32_16x16x4_f32 v[16:19], v39, v97, v[16:19]
	s_waitcnt vmcnt(0)
; template <int NS>
; DI_ void skinny_pass_bf16(const bf16_t* XBrows, int nrows, const float* WsT, float* sk_out, int gw, int NGW, int lane) {
;     ...
;                 for (int j = 0; j < 4; ++j) { const f32x4 w = *(const f32x4*)(wp + 256 * j);
;                     s0 += (v[0][4 * j] * w[0] + v[0][4 * j + 1] * w[1]) + (v[0][4 * j + 2] * w[2] + v[0][4 * j + 3] * w[3]);
;                     s1 += (v[1][4 * j] * w[0] + v[1][4 * j + 1] * w[1]) + (v[1][4 * j + 2] * w[2] + v[1][4 * j + 3] * w[3]);
;                     s2 += (v[2][4 * j] * w[0] + v[2][4 * j + 1] * w[1]) + (v[2][4 * j + 2] * w[2] + v[2][4 * j + 3] * w[3]);
;                     s3 += (v[3][4 * j] * w[0] + v[3][4 * j + 1] * w[1]) + (v[3][4 * j + 2] * w[2] + v[3][4 * j + 3] * w[3]); }
;                 a[0][jc] = s0; a[1][jc] = s1; a[2][jc] = s2; a[3][jc] = s3;
;             }
; #pragma unroll
;             for (int r = 0; r < 4; ++r) {
;                 { const bool up = (lane & 32) != 0;
; #pragma unroll
;                   for (int i = 0; i < 4; ++i) { const float send = up ? a[r][i] : a[r][4 + i], keep = up ? a[r][4 + i] : a[r][i]; a[r][i] = keep + __shfl_xor(send, 32); } }
;                 { const bool up = (lane & 16) != 0;
; #pragma unroll
;                   for (int i = 0; i < 2; ++i) { const float send = up ? a[r][i] : a[r][2 + i], keep = up ? a[r][2 + i] : a[r][i]; a[r][i] = keep + __shfl_xor(send, 16); } }
;                 { const bool up = (lane & 8) != 0; const float send = up ? a[r][0] : a[r][1], keep = up ? a[r][1] : a[r][0]; a[r][0] = keep + __shfl_xor(send, 8); }
;                 a[r][0] += __shfl_xor(a[r][0], 4); a[r][0] += __shfl_xor(a[r][0], 2); a[r][0] += __shfl_xor(a[r][0], 1);
;                 if ((lane & 7) == 0 && row + r * NGW < nrows) sk_out[(size_t)(row + r * NGW) * NS + 8 * grp + (lane >> 3)] = a[r][0];
	s_waitcnt lgkmcnt(0)
	v_lshlrev_b32_e32 v36, 16, v50
	v_and_b32_e32 v37, 0xffff0000, v50
	v_lshlrev_b32_e32 v38, 16, v51
	v_mfma_f32_16x16x4_f32 v[12:15], v36, v98, v[12:15]
	v_and_b32_e32 v39, 0xffff0000, v51
	v_mfma_f32_16x16x4_f32 v[16:19], v37, v99, v[16:19]
	v_lshlrev_b32_e32 v36, 16, v52
	v_mfma_f32_16x16x4_f32 v[12:15], v38, v100, v[12:15]
	v_and_b32_e32 v37, 0xffff0000, v52
	v_mfma_f32_16x16x4_f32 v[16:19], v39, v101, v[16:19]
	v_lshlrev_b32_e32 v38, 16, v53
	v_mfma_f32_16x16x4_f32 v[12:15], v36, v102, v[12:15]
	v_and_b32_e32 v39, 0xffff0000, v53
	v_mfma_f32_16x16x4_f32 v[16:19], v37, v103, v[16:19]
	v_lshlrev_b32_e32 v36, 16, v54
	v_mfma_f32_16x16x4_f32 v[12:15], v38, v104, v[12:15]
	v_and_b32_e32 v37, 0xffff0000, v54
	v_mfma_f32_16x16x4_f32 v[16:19], v39, v105, v[16:19]
	v_lshlrev_b32_e32 v38, 16, v55
	v_mfma_f32_16x16x4_f32 v[12:15], v36, v106, v[12:15]
	v_and_b32_e32 v39, 0xffff0000, v55
	v_mfma_f32_16x16x4_f32 v[16:19], v37, v107, v[16:19]
	v_lshlrev_b32_e32 v36, 16, v56
	v_mfma_f32_16x16x4_f32 v[12:15], v38, v108, v[12:15]
	v_and_b32_e32 v37, 0xffff0000, v56
	v_mfma_f32_16x16x4_f32 v[16:19], v39, v109, v[16:19]
	v_lshlrev_b32_e32 v38, 16, v57
	v_mfma_f32_16x16x4_f32 v[12:15], v36, v110, v[12:15]
	v_and_b32_e32 v39, 0xffff0000, v57
	v_mfma_f32_16x16x4_f32 v[16:19], v37, v111, v[16:19]
	v_lshlrev_b32_e32 v36, 16, v58
	v_mfma_f32_16x16x4_f32 v[12:15], v38, v112, v[12:15]
	v_and_b32_e32 v37, 0xffff0000, v58
	v_mfma_f32_16x16x4_f32 v[16:19], v39, v113, v[16:19]
	v_lshlrev_b32_e32 v38, 16, v59
	v_mfma_f32_16x16x4_f32 v[12:15], v36, v114, v[12:15]
	v_and_b32_e32 v39, 0xffff0000, v59
	v_mfma_f32_16x16x4_f32 v[16:19], v37, v115, v[16:19]
	v_lshlrev_b32_e32 v36, 16, v60
	v_mfma_f32_16x16x4_f32 v[12:15], v38, v116, v[12:15]
	v_and_b32_e32 v37, 0xffff0000, v60
	v_mfma_f32_16x16x4_f32 v[16:19], v39, v117, v[16:19]
	v_lshlrev_b32_e32 v38, 16, v61
	v_mfma_f32_16x16x4_f32 v[12:15], v36, v118, v[12:15]
	v_and_b32_e32 v39, 0xffff0000, v61
	v_mfma_f32_16x16x4_f32 v[16:19], v37, v119, v[16:19]
	v_lshlrev_b32_e32 v36, 16, v62
	v_mfma_f32_16x16x4_f32 v[12:15], v38, v120, v[12:15]
	v_and_b32_e32 v37, 0xffff0000, v62
	v_mfma_f32_16x16x4_f32 v[16:19], v39, v121, v[16:19]
	v_lshlrev_b32_e32 v38, 16, v63
	v_mfma_f32_16x16x4_f32 v[12:15], v36, v122, v[12:15]
	v_and_b32_e32 v39, 0xffff0000, v63
	v_mfma_f32_16x16x4_f32 v[16:19], v37, v123, v[16:19]
	v_lshlrev_b32_e32 v36, 16, v64
	v_mfma_f32_16x16x4_f32 v[12:15], v38, v124, v[12:15]
	v_and_b32_e32 v37, 0xffff0000, v64
	v_mfma_f32_16x16x4_f32 v[16:19], v39, v125, v[16:19]
	v_lshlrev_b32_e32 v38, 16, v65
	v_mfma_f32_16x16x4_f32 v[12:15], v36, v126, v[12:15]
	v_and_b32_e32 v39, 0xffff0000, v65
	v_mfma_f32_16x16x4_f32 v[16:19], v37, v127, v[16:19]
	s_nop 0
	v_mfma_f32_16x16x4_f32 v[12:15], v38, v128, v[12:15]
	s_nop 0
	v_mfma_f32_16x16x4_f32 v[16:19], v39, v129, v[16:19]
	s_nop 15
	v_add_f32_e32 v12, v12, v16
	v_add_f32_e32 v13, v13, v17
	v_add_f32_e32 v14, v14, v18
	v_add_f32_e32 v15, v15, v19
	global_store_dword v[10:11], v12, off
	global_store_dword v[10:11], v13, off offset:128
	global_store_dword v[10:11], v14, off offset:256
	global_store_dword v[10:11], v15, off offset:384
	s_branch .LBB0_481
.Lmy_sk_orig:
	v_and_b32_e32 v1, 63, v0
	v_lshlrev_b32_e32 v2, 3, v1
	v_lshl_add_u32 v49, v1, 4, 0
	v_cmp_gt_u32_e32 vcc, 32, v1
	v_xor_b32_e32 v1, 32, v192
	v_cmp_lt_i32_e64 s[0:1], v1, v193
	v_mov_b32_e32 v3, v48
	v_lshl_add_u64 v[130:131], s[54:55], 0, v[2:3]
	v_cndmask_b32_e64 v1, v192, v1, s[0:1]
	v_lshlrev_b32_e32 v142, 2, v1
	v_and_b32_e32 v1, 16, v0
	v_cmp_eq_u32_e64 s[38:39], 0, v1
	v_xor_b32_e32 v1, 16, v192
	v_cmp_lt_i32_e64 s[0:1], v1, v193
	s_nop 1
	v_cndmask_b32_e64 v1, v192, v1, s[0:1]
	v_lshlrev_b32_e32 v143, 2, v1
	v_and_b32_e32 v1, 8, v0
	v_cmp_eq_u32_e64 s[42:43], 0, v1
	v_xor_b32_e32 v1, 8, v192
	v_cmp_lt_i32_e64 s[0:1], v1, v193
	s_nop 1
	v_cndmask_b32_e64 v1, v192, v1, s[0:1]
	v_lshlrev_b32_e32 v144, 2, v1
	v_xor_b32_e32 v1, 4, v192
	v_cmp_lt_i32_e64 s[0:1], v1, v193
	s_nop 1
	v_cndmask_b32_e64 v1, v192, v1, s[0:1]
	v_lshlrev_b32_e32 v145, 2, v1
	v_xor_b32_e32 v1, 2, v192
	v_cmp_lt_i32_e64 s[0:1], v1, v193
	s_nop 1
	v_cndmask_b32_e64 v1, v192, v1, s[0:1]
	v_cmp_lt_i32_e64 s[0:1], v250, v193
	v_lshlrev_b32_e32 v146, 2, v1
	s_nop 0
	v_cndmask_b32_e64 v1, v192, v250, s[0:1]
	v_lshlrev_b32_e32 v147, 2, v1
	v_and_b32_e32 v1, 7, v0
	v_lshrrev_b32_e32 v0, 1, v0
	v_readlane_b32 s1, v254, 7
	v_cmp_ne_u32_e64 s[44:45], 0, v1
	v_cmp_eq_u32_e64 s[46:47], 0, v1
	v_and_b32_e32 v0, 28, v0
	v_mov_b32_e32 v1, v48
	v_readlane_b32 s0, v254, 5
	s_add_i32 s6, s1, s4
	v_readlane_b32 s1, v254, 4
	v_lshl_add_u64 v[132:133], s[28:29], 0, v[0:1]
	s_add_i32 s0, s0, s4
	s_add_i32 s50, s1, s4
	s_branch .LBB0_471
